# removed the redundant s_setprio 0/1 pair between the two MFMA blocks of each GEMM super-phase
# speedup vs baseline: 1.0045x; 1.0012x over previous
; #define PG8_STAGE(bufoff, gbase, voff) do { _Pragma("unroll") for (int _i = 0; _i < 2; ++_i) \
;         __builtin_amdgcn_global_load_lds((const unsigned*)((const char*)(gbase) + (voff)[_i]), (PG8_LAS unsigned*)(lds + (bufoff) + ldsw + _i * 8192), 16, 0, 0); } while (0)
; #define PG8_LDA(dst, b, h) do { _Pragma("unroll") for (int m = 0; m < 4; ++m) _Pragma("unroll") for (int k = 0; k < 2; ++k) dst[m][k] = *(const PG8_LAS bf16x8*)(lds + PG8_SA(b, h) + aoff + m * 2048 + k * 1024); } while (0)
; #define PG8_LDB(dst, b, h) do { _Pragma("unroll") for (int n = 0; n < 2; ++n) _Pragma("unroll") for (int k = 0; k < 2; ++k) dst[n][k] = *(const PG8_LAS bf16x8*)(lds + PG8_SB(b, h) + boff + n * 2048 + k * 1024); } while (0)
; #define PG8_MMA(ai, bj, At, Bt) do { __builtin_amdgcn_s_setprio(1); _Pragma("unroll") for (int m = 0; m < 4; ++m) _Pragma("unroll") for (int n = 0; n < 2; ++n) _Pragma("unroll") for (int k = 0; k < 2; ++k) \
;         acc[ai][bj][m][n] = __builtin_amdgcn_mfma_f32_16x16x32_bf16(Bt[n][k], At[m][k], acc[ai][bj][m][n], 0, 0, 0); __builtin_amdgcn_s_setprio(0); } while (0)
; #define PG8_WAIT_V(n) asm volatile("s_waitcnt vmcnt(" #n ")" ::: "memory")
; #define PG8_WAIT_L(n) asm volatile("s_waitcnt lgkmcnt(" #n ")" ::: "memory")
; template <class Epi, class Sched, bool ALIGN_EPI = false, bool SP2 = false>
; __device__ __forceinline__ void gemm_phase(PG8_LAS unsigned char* lds, const Gemm g, const Sched& S, const Epi& E) {
;     ...
;             const bool last = (t == nt - 2);
;             const char* a1 = cA + (size_t)(t + 1) * kstep;
;             const char* a2 = last ? nA : cA + (size_t)(t + 2) * kstep; const char* b2 = last ? nB : cB + (size_t)(t + 2) * kstep;
;             const char* a3 = a2 + kstep; const char* b3 = b2 + kstep;
;             if (last && has_next) S.a_ready(nxt, ui + 1);
;             if constexpr (SP2) {
;             PG8_LDB(B0, 0, 0); PG8_LDB(B1, 0, 1); PG8_SCHED; PG8_LDA(At, 0, 0); PG8_STAGE(PG8_SA(1, 1), a1 + hstep, voffA);
;             PG8_WAIT_V(8); PG8_WAIT_L(0); PG8_BAR; PG8_MMA(0, 0, At, B0); PG8_MMA(0, 1, At, B1); PG8_BAR; PG8_SCHED;
;             PG8_LDA(At, 0, 1); PG8_STAGE(PG8_SB(0, 0), b2, voffB); PG8_STAGE(PG8_SB(0, 1), b2 + hstep, voffB); PG8_STAGE(PG8_SA(0, 0), a2, voffA);
;             PG8_WAIT_V(8); PG8_WAIT_L(0); PG8_BAR; PG8_MMA(1, 0, At, B0); PG8_MMA(1, 1, At, B1); PG8_BAR; PG8_SCHED;
.LBB0_337:
	ds_read_b128 v[152:155], v148
	ds_read_b128 v[156:159], v148 offset:1024
	ds_read_b128 v[160:163], v148 offset:2048
	ds_read_b128 v[164:167], v148 offset:3072
	ds_read_b128 v[168:171], v149
	ds_read_b128 v[172:175], v149 offset:1024
	ds_read_b128 v[176:179], v149 offset:2048
	ds_read_b128 v[180:183], v149 offset:3072
	s_add_u32 s26, s24, 0xfffc0080
	s_addc_u32 s27, s25, -1
	s_cmp_eq_u32 s54, 12
	s_cselect_b32 s29, s17, s27
	s_cselect_b32 s28, s50, s26
	s_cselect_b32 s27, s15, s53
	s_cselect_b32 s26, s51, s52
	v_lshl_add_u64 v[216:217], s[24:25], 0, v[136:137]
	s_add_i32 m0, s23, 0xc000
	ds_read_b128 v[184:187], v150
	ds_read_b128 v[188:191], v150 offset:1024
	ds_read_b128 v[192:195], v150 offset:2048
	ds_read_b128 v[196:199], v150 offset:3072
	ds_read_b128 v[200:203], v150 offset:4096
	ds_read_b128 v[204:207], v150 offset:5120
	ds_read_b128 v[208:211], v150 offset:6144
	ds_read_b128 v[212:215], v150 offset:7168
	global_load_lds_dwordx4 v[216:217], off
	v_lshl_add_u64 v[216:217], s[24:25], 0, v[138:139]
	s_add_i32 m0, s23, 0xe000
	s_nop 0
	global_load_lds_dwordx4 v[216:217], off
	s_waitcnt vmcnt(8)
	s_waitcnt lgkmcnt(0)
	s_barrier
	s_setprio 1
	s_waitcnt lgkmcnt(0)
	v_mfma_f32_16x16x32_bf16 v[124:127], v[152:155], v[184:187], v[124:127]
	v_mfma_f32_16x16x32_bf16 v[120:123], v[160:163], v[184:187], v[120:123]
	v_mfma_f32_16x16x32_bf16 v[108:111], v[152:155], v[192:195], v[108:111]
	v_mfma_f32_16x16x32_bf16 v[104:107], v[160:163], v[192:195], v[104:107]
	v_mfma_f32_16x16x32_bf16 v[92:95], v[152:155], v[200:203], v[92:95]
	v_mfma_f32_16x16x32_bf16 v[88:91], v[160:163], v[200:203], v[88:91]
	v_mfma_f32_16x16x32_bf16 v[76:79], v[152:155], v[208:211], v[76:79]
	v_mfma_f32_16x16x32_bf16 v[72:75], v[160:163], v[208:211], v[72:75]
	v_mfma_f32_16x16x32_bf16 v[124:127], v[156:159], v[188:191], v[124:127]
	v_mfma_f32_16x16x32_bf16 v[120:123], v[164:167], v[188:191], v[120:123]
	v_mfma_f32_16x16x32_bf16 v[108:111], v[156:159], v[196:199], v[108:111]
	v_mfma_f32_16x16x32_bf16 v[104:107], v[164:167], v[196:199], v[104:107]
	v_mfma_f32_16x16x32_bf16 v[92:95], v[156:159], v[204:207], v[92:95]
	v_mfma_f32_16x16x32_bf16 v[88:91], v[164:167], v[204:207], v[88:91]
	v_mfma_f32_16x16x32_bf16 v[76:79], v[156:159], v[212:215], v[76:79]
	v_mfma_f32_16x16x32_bf16 v[72:75], v[164:167], v[212:215], v[72:75]
	v_mfma_f32_16x16x32_bf16 v[116:119], v[168:171], v[184:187], v[116:119]
	v_mfma_f32_16x16x32_bf16 v[112:115], v[176:179], v[184:187], v[112:115]
	v_mfma_f32_16x16x32_bf16 v[100:103], v[168:171], v[192:195], v[100:103]
	v_mfma_f32_16x16x32_bf16 v[96:99], v[176:179], v[192:195], v[96:99]
	v_mfma_f32_16x16x32_bf16 v[84:87], v[168:171], v[200:203], v[84:87]
	v_mfma_f32_16x16x32_bf16 v[80:83], v[176:179], v[200:203], v[80:83]
	v_mfma_f32_16x16x32_bf16 v[68:71], v[168:171], v[208:211], v[68:71]
	v_mfma_f32_16x16x32_bf16 v[64:67], v[176:179], v[208:211], v[64:67]
	v_mfma_f32_16x16x32_bf16 v[116:119], v[172:175], v[188:191], v[116:119]
	v_mfma_f32_16x16x32_bf16 v[112:115], v[180:183], v[188:191], v[112:115]
	v_mfma_f32_16x16x32_bf16 v[100:103], v[172:175], v[196:199], v[100:103]
	v_mfma_f32_16x16x32_bf16 v[96:99], v[180:183], v[196:199], v[96:99]
	v_mfma_f32_16x16x32_bf16 v[84:87], v[172:175], v[204:207], v[84:87]
	v_mfma_f32_16x16x32_bf16 v[80:83], v[180:183], v[204:207], v[80:83]
	v_mfma_f32_16x16x32_bf16 v[68:71], v[172:175], v[212:215], v[68:71]
	v_mfma_f32_16x16x32_bf16 v[64:67], v[180:183], v[212:215], v[64:67]
	s_setprio 0
	s_barrier
	s_add_i32 s55, s44, s33
	v_lshl_add_u64 v[216:217], s[26:27], 0, v[132:133]
	s_mov_b32 m0, s55
	ds_read_b128 v[184:187], v150 offset:16384
	ds_read_b128 v[188:191], v150 offset:17408
	ds_read_b128 v[192:195], v150 offset:18432
	ds_read_b128 v[196:199], v150 offset:19456
	ds_read_b128 v[200:203], v150 offset:20480
	ds_read_b128 v[204:207], v150 offset:21504
	ds_read_b128 v[208:211], v150 offset:22528
	ds_read_b128 v[212:215], v150 offset:23552
	global_load_lds_dwordx4 v[216:217], off
	s_add_i32 m0, s55, 0x2000
	s_add_u32 s56, s26, 0x40000
	v_lshl_add_u64 v[218:219], s[26:27], 0, v[128:129]
	s_addc_u32 s57, s27, 0
	s_add_i32 s55, s45, s33
	global_load_lds_dwordx4 v[218:219], off
	v_lshl_add_u64 v[220:221], s[56:57], 0, v[132:133]
	s_mov_b32 m0, s55
	v_lshl_add_u64 v[222:223], s[28:29], 0, v[130:131]
	global_load_lds_dwordx4 v[220:221], off
	v_lshl_add_u64 v[220:221], s[56:57], 0, v[128:129]
	s_add_i32 m0, s55, 0x2000
	s_nop 0
	global_load_lds_dwordx4 v[220:221], off
	v_lshl_add_u64 v[220:221], s[28:29], 0, v[134:135]
	s_mov_b32 m0, s23
	s_nop 0
	global_load_lds_dwordx4 v[220:221], off
	s_mov_b32 m0, s39
	s_nop 0
	global_load_lds_dwordx4 v[222:223], off
	s_waitcnt vmcnt(8)
	s_waitcnt lgkmcnt(0)
	s_barrier
; #define PG8_STAGE(bufoff, gbase, voff) do { _Pragma("unroll") for (int _i = 0; _i < 2; ++_i) \
;         __builtin_amdgcn_global_load_lds((const unsigned*)((const char*)(gbase) + (voff)[_i]), (PG8_LAS unsigned*)(lds + (bufoff) + ldsw + _i * 8192), 16, 0, 0); } while (0)
; #define PG8_LDA(dst, b, h) do { _Pragma("unroll") for (int m = 0; m < 4; ++m) _Pragma("unroll") for (int k = 0; k < 2; ++k) dst[m][k] = *(const PG8_LAS bf16x8*)(lds + PG8_SA(b, h) + aoff + m * 2048 + k * 1024); } while (0)
; #define PG8_LDB(dst, b, h) do { _Pragma("unroll") for (int n = 0; n < 2; ++n) _Pragma("unroll") for (int k = 0; k < 2; ++k) dst[n][k] = *(const PG8_LAS bf16x8*)(lds + PG8_SB(b, h) + boff + n * 2048 + k * 1024); } while (0)
; #define PG8_MMA(ai, bj, At, Bt) do { __builtin_amdgcn_s_setprio(1); _Pragma("unroll") for (int m = 0; m < 4; ++m) _Pragma("unroll") for (int n = 0; n < 2; ++n) _Pragma("unroll") for (int k = 0; k < 2; ++k) \
;         acc[ai][bj][m][n] = __builtin_amdgcn_mfma_f32_16x16x32_bf16(Bt[n][k], At[m][k], acc[ai][bj][m][n], 0, 0, 0); __builtin_amdgcn_s_setprio(0); } while (0)
; #define PG8_WAIT_V(n) asm volatile("s_waitcnt vmcnt(" #n ")" ::: "memory")
; #define PG8_WAIT_L(n) asm volatile("s_waitcnt lgkmcnt(" #n ")" ::: "memory")
; #define PG8_BAR __builtin_amdgcn_s_barrier()
; #define PG8_SCHED __builtin_amdgcn_sched_barrier(0)
; template <class Epi, class Sched, bool ALIGN_EPI = false, bool SP2 = false>
; __device__ __forceinline__ void gemm_phase(PG8_LAS unsigned char* lds, const Gemm g, const Sched& S, const Epi& E) {
;     ...
;             PG8_WAIT_V(8); PG8_WAIT_L(0); PG8_BAR; PG8_MMA(1, 0, At, B0); PG8_MMA(1, 1, At, B1); PG8_BAR; PG8_SCHED;
;             PG8_LDB(B0, 1, 0); PG8_LDB(B1, 1, 1); PG8_SCHED; PG8_LDA(At, 1, 0); PG8_STAGE(PG8_SA(0, 1), a2 + hstep, voffA);
;             PG8_WAIT_V(8); PG8_WAIT_L(0); PG8_BAR; PG8_MMA(0, 0, At, B0); PG8_MMA(0, 1, At, B1); PG8_BAR; PG8_SCHED;
	s_setprio 1
	s_waitcnt lgkmcnt(0)
	v_mfma_f32_16x16x32_bf16 v[60:63], v[152:155], v[184:187], v[60:63]
	v_mfma_f32_16x16x32_bf16 v[56:59], v[160:163], v[184:187], v[56:59]
	v_mfma_f32_16x16x32_bf16 v[44:47], v[152:155], v[192:195], v[44:47]
	v_mfma_f32_16x16x32_bf16 v[40:43], v[160:163], v[192:195], v[40:43]
	v_mfma_f32_16x16x32_bf16 v[28:31], v[152:155], v[200:203], v[28:31]
	v_mfma_f32_16x16x32_bf16 v[24:27], v[160:163], v[200:203], v[24:27]
	v_mfma_f32_16x16x32_bf16 v[12:15], v[152:155], v[208:211], v[12:15]
	v_mfma_f32_16x16x32_bf16 v[8:11], v[160:163], v[208:211], v[8:11]
	v_mfma_f32_16x16x32_bf16 v[60:63], v[156:159], v[188:191], v[60:63]
	v_mfma_f32_16x16x32_bf16 v[56:59], v[164:167], v[188:191], v[56:59]
	v_mfma_f32_16x16x32_bf16 v[44:47], v[156:159], v[196:199], v[44:47]
	v_mfma_f32_16x16x32_bf16 v[40:43], v[164:167], v[196:199], v[40:43]
	v_mfma_f32_16x16x32_bf16 v[28:31], v[156:159], v[204:207], v[28:31]
	v_mfma_f32_16x16x32_bf16 v[24:27], v[164:167], v[204:207], v[24:27]
	v_mfma_f32_16x16x32_bf16 v[12:15], v[156:159], v[212:215], v[12:15]
	v_mfma_f32_16x16x32_bf16 v[8:11], v[164:167], v[212:215], v[8:11]
	v_mfma_f32_16x16x32_bf16 v[52:55], v[168:171], v[184:187], v[52:55]
	v_mfma_f32_16x16x32_bf16 v[48:51], v[176:179], v[184:187], v[48:51]
	v_mfma_f32_16x16x32_bf16 v[36:39], v[168:171], v[192:195], v[36:39]
	v_mfma_f32_16x16x32_bf16 v[32:35], v[176:179], v[192:195], v[32:35]
	v_mfma_f32_16x16x32_bf16 v[20:23], v[168:171], v[200:203], v[20:23]
	v_mfma_f32_16x16x32_bf16 v[16:19], v[176:179], v[200:203], v[16:19]
	v_mfma_f32_16x16x32_bf16 v[4:7], v[168:171], v[208:211], v[4:7]
	v_mfma_f32_16x16x32_bf16 v[0:3], v[176:179], v[208:211], v[0:3]
	v_mfma_f32_16x16x32_bf16 v[52:55], v[172:175], v[188:191], v[52:55]
	v_mfma_f32_16x16x32_bf16 v[48:51], v[180:183], v[188:191], v[48:51]
	v_mfma_f32_16x16x32_bf16 v[36:39], v[172:175], v[196:199], v[36:39]
	v_mfma_f32_16x16x32_bf16 v[32:35], v[180:183], v[196:199], v[32:35]
	v_mfma_f32_16x16x32_bf16 v[20:23], v[172:175], v[204:207], v[20:23]
	v_mfma_f32_16x16x32_bf16 v[16:19], v[180:183], v[204:207], v[16:19]
	v_mfma_f32_16x16x32_bf16 v[4:7], v[172:175], v[212:215], v[4:7]
	v_mfma_f32_16x16x32_bf16 v[0:3], v[180:183], v[212:215], v[0:3]
	s_setprio 0
	s_barrier
	s_add_i32 s55, 0, 0x18000
	v_add_u32_e32 v151, s55, v145
	s_add_i32 s56, 0, 0x1c000
	ds_read_b128 v[152:155], v151
	ds_read_b128 v[156:159], v151 offset:1024
	ds_read_b128 v[160:163], v151 offset:2048
	ds_read_b128 v[164:167], v151 offset:3072
	v_add_u32_e32 v151, s56, v145
	ds_read_b128 v[168:171], v151
	ds_read_b128 v[172:175], v151 offset:1024
	ds_read_b128 v[176:179], v151 offset:2048
	ds_read_b128 v[180:183], v151 offset:3072
	s_add_u32 s28, s28, 0x40000
	s_addc_u32 s29, s29, 0
	s_mov_b32 m0, s40
	v_lshl_add_u64 v[224:225], s[28:29], 0, v[134:135]
	ds_read_b128 v[184:187], v150 offset:32768
	ds_read_b128 v[188:191], v150 offset:33792
	ds_read_b128 v[192:195], v150 offset:34816
	ds_read_b128 v[196:199], v150 offset:35840
	ds_read_b128 v[200:203], v150 offset:36864
	ds_read_b128 v[204:207], v150 offset:37888
	ds_read_b128 v[208:211], v150 offset:38912
	ds_read_b128 v[212:215], v150 offset:39936
	global_load_lds_dwordx4 v[224:225], off
	v_lshl_add_u64 v[224:225], s[28:29], 0, v[130:131]
	s_mov_b32 m0, s41
	s_nop 0
	global_load_lds_dwordx4 v[224:225], off
	s_waitcnt vmcnt(8)
	s_waitcnt lgkmcnt(0)
	s_barrier
	s_setprio 1
	s_waitcnt lgkmcnt(0)
	v_mfma_f32_16x16x32_bf16 v[124:127], v[152:155], v[184:187], v[124:127]
	v_mfma_f32_16x16x32_bf16 v[120:123], v[160:163], v[184:187], v[120:123]
	v_mfma_f32_16x16x32_bf16 v[108:111], v[152:155], v[192:195], v[108:111]
	v_mfma_f32_16x16x32_bf16 v[104:107], v[160:163], v[192:195], v[104:107]
	v_mfma_f32_16x16x32_bf16 v[92:95], v[152:155], v[200:203], v[92:95]
	v_mfma_f32_16x16x32_bf16 v[88:91], v[160:163], v[200:203], v[88:91]
	v_mfma_f32_16x16x32_bf16 v[76:79], v[152:155], v[208:211], v[76:79]
	v_mfma_f32_16x16x32_bf16 v[72:75], v[160:163], v[208:211], v[72:75]
	v_mfma_f32_16x16x32_bf16 v[124:127], v[156:159], v[188:191], v[124:127]
	v_mfma_f32_16x16x32_bf16 v[120:123], v[164:167], v[188:191], v[120:123]
	v_mfma_f32_16x16x32_bf16 v[108:111], v[156:159], v[196:199], v[108:111]
	v_mfma_f32_16x16x32_bf16 v[104:107], v[164:167], v[196:199], v[104:107]
	v_mfma_f32_16x16x32_bf16 v[92:95], v[156:159], v[204:207], v[92:95]
	v_mfma_f32_16x16x32_bf16 v[88:91], v[164:167], v[204:207], v[88:91]
	v_mfma_f32_16x16x32_bf16 v[76:79], v[156:159], v[212:215], v[76:79]
	v_mfma_f32_16x16x32_bf16 v[72:75], v[164:167], v[212:215], v[72:75]
	v_mfma_f32_16x16x32_bf16 v[116:119], v[168:171], v[184:187], v[116:119]
	v_mfma_f32_16x16x32_bf16 v[112:115], v[176:179], v[184:187], v[112:115]
	v_mfma_f32_16x16x32_bf16 v[100:103], v[168:171], v[192:195], v[100:103]
	v_mfma_f32_16x16x32_bf16 v[96:99], v[176:179], v[192:195], v[96:99]
	v_mfma_f32_16x16x32_bf16 v[84:87], v[168:171], v[200:203], v[84:87]
	v_mfma_f32_16x16x32_bf16 v[80:83], v[176:179], v[200:203], v[80:83]
	v_mfma_f32_16x16x32_bf16 v[68:71], v[168:171], v[208:211], v[68:71]
	v_mfma_f32_16x16x32_bf16 v[64:67], v[176:179], v[208:211], v[64:67]
	v_mfma_f32_16x16x32_bf16 v[116:119], v[172:175], v[188:191], v[116:119]
	v_mfma_f32_16x16x32_bf16 v[112:115], v[180:183], v[188:191], v[112:115]
	v_mfma_f32_16x16x32_bf16 v[100:103], v[172:175], v[196:199], v[100:103]
	v_mfma_f32_16x16x32_bf16 v[96:99], v[180:183], v[196:199], v[96:99]
	v_mfma_f32_16x16x32_bf16 v[84:87], v[172:175], v[204:207], v[84:87]
	v_mfma_f32_16x16x32_bf16 v[80:83], v[180:183], v[204:207], v[80:83]
	v_mfma_f32_16x16x32_bf16 v[68:71], v[172:175], v[212:215], v[68:71]
	v_mfma_f32_16x16x32_bf16 v[64:67], v[180:183], v[212:215], v[64:67]
	s_setprio 0
	s_barrier
; #define PG8_STAGE(bufoff, gbase, voff) do { _Pragma("unroll") for (int _i = 0; _i < 2; ++_i) \
;         __builtin_amdgcn_global_load_lds((const unsigned*)((const char*)(gbase) + (voff)[_i]), (PG8_LAS unsigned*)(lds + (bufoff) + ldsw + _i * 8192), 16, 0, 0); } while (0)
; #define PG8_LDA(dst, b, h) do { _Pragma("unroll") for (int m = 0; m < 4; ++m) _Pragma("unroll") for (int k = 0; k < 2; ++k) dst[m][k] = *(const PG8_LAS bf16x8*)(lds + PG8_SA(b, h) + aoff + m * 2048 + k * 1024); } while (0)
; #define PG8_MMA(ai, bj, At, Bt) do { __builtin_amdgcn_s_setprio(1); _Pragma("unroll") for (int m = 0; m < 4; ++m) _Pragma("unroll") for (int n = 0; n < 2; ++n) _Pragma("unroll") for (int k = 0; k < 2; ++k) \
;         acc[ai][bj][m][n] = __builtin_amdgcn_mfma_f32_16x16x32_bf16(Bt[n][k], At[m][k], acc[ai][bj][m][n], 0, 0, 0); __builtin_amdgcn_s_setprio(0); } while (0)
; #define PG8_WAIT_V(n) asm volatile("s_waitcnt vmcnt(" #n ")" ::: "memory")
; #define PG8_WAIT_L(n) asm volatile("s_waitcnt lgkmcnt(" #n ")" ::: "memory")
; #define PG8_BAR __builtin_amdgcn_s_barrier()
; #define PG8_SCHED __builtin_amdgcn_sched_barrier(0)
; template <class Epi, class Sched, bool ALIGN_EPI = false, bool SP2 = false>
; __device__ __forceinline__ void gemm_phase(PG8_LAS unsigned char* lds, const Gemm g, const Sched& S, const Epi& E) {
;     ...
;             PG8_LDA(At, 1, 1); PG8_STAGE(PG8_SB(1, 0), b3, voffB); PG8_STAGE(PG8_SB(1, 1), b3 + hstep, voffB); PG8_STAGE(PG8_SA(1, 0), a3, voffA);
;             PG8_WAIT_V(8); PG8_WAIT_L(0); PG8_BAR; PG8_MMA(1, 0, At, B0); PG8_MMA(1, 1, At, B1); PG8_BAR; PG8_SCHED;
;     ...
;         if constexpr (ALIGN_EPI) { if (wr == 0) PG8_BAR; }
;         if constexpr (!Epi::AFTER_DRAIN) { E(acc, cur, wr, wc, fr, fq, ui); S.done(cur); }
;         if (!has_next) break;
	s_add_i32 s28, s55, s33
	v_lshl_add_u64 v[216:217], v[216:217], 0, s[8:9]
	s_mov_b32 m0, s28
	ds_read_b128 v[184:187], v150 offset:49152
	ds_read_b128 v[188:191], v150 offset:50176
	ds_read_b128 v[192:195], v150 offset:51200
	ds_read_b128 v[196:199], v150 offset:52224
	ds_read_b128 v[200:203], v150 offset:53248
	ds_read_b128 v[204:207], v150 offset:54272
	ds_read_b128 v[208:211], v150 offset:55296
	ds_read_b128 v[212:215], v150 offset:56320
	global_load_lds_dwordx4 v[216:217], off
	s_add_i32 m0, s28, 0x2000
	s_add_u32 s26, s26, 0x40080
	v_lshl_add_u64 v[216:217], v[218:219], 0, s[8:9]
	s_addc_u32 s27, s27, 0
	s_add_i32 s28, s56, s33
	global_load_lds_dwordx4 v[216:217], off
	v_lshl_add_u64 v[216:217], s[26:27], 0, v[132:133]
	s_mov_b32 m0, s28
	s_nop 0
	global_load_lds_dwordx4 v[216:217], off
	v_lshl_add_u64 v[216:217], s[26:27], 0, v[128:129]
	s_add_i32 m0, s28, 0x2000
	s_nop 0
	global_load_lds_dwordx4 v[216:217], off
	v_lshl_add_u64 v[216:217], v[220:221], 0, s[8:9]
	s_mov_b32 m0, s42
	s_nop 0
	global_load_lds_dwordx4 v[216:217], off
	v_lshl_add_u64 v[216:217], v[222:223], 0, s[8:9]
	s_mov_b32 m0, s43
	s_nop 0
	global_load_lds_dwordx4 v[216:217], off
	s_waitcnt vmcnt(8)
	s_waitcnt lgkmcnt(0)
	s_barrier
	s_setprio 1
	s_waitcnt lgkmcnt(0)
	v_mfma_f32_16x16x32_bf16 v[60:63], v[152:155], v[184:187], v[60:63]
	v_mfma_f32_16x16x32_bf16 v[56:59], v[160:163], v[184:187], v[56:59]
	v_mfma_f32_16x16x32_bf16 v[44:47], v[152:155], v[192:195], v[44:47]
	v_mfma_f32_16x16x32_bf16 v[40:43], v[160:163], v[192:195], v[40:43]
	v_mfma_f32_16x16x32_bf16 v[28:31], v[152:155], v[200:203], v[28:31]
	v_mfma_f32_16x16x32_bf16 v[24:27], v[160:163], v[200:203], v[24:27]
	v_mfma_f32_16x16x32_bf16 v[12:15], v[152:155], v[208:211], v[12:15]
	v_mfma_f32_16x16x32_bf16 v[8:11], v[160:163], v[208:211], v[8:11]
	v_mfma_f32_16x16x32_bf16 v[60:63], v[156:159], v[188:191], v[60:63]
	v_mfma_f32_16x16x32_bf16 v[56:59], v[164:167], v[188:191], v[56:59]
	v_mfma_f32_16x16x32_bf16 v[44:47], v[156:159], v[196:199], v[44:47]
	v_mfma_f32_16x16x32_bf16 v[40:43], v[164:167], v[196:199], v[40:43]
	v_mfma_f32_16x16x32_bf16 v[28:31], v[156:159], v[204:207], v[28:31]
	v_mfma_f32_16x16x32_bf16 v[24:27], v[164:167], v[204:207], v[24:27]
	v_mfma_f32_16x16x32_bf16 v[12:15], v[156:159], v[212:215], v[12:15]
	v_mfma_f32_16x16x32_bf16 v[8:11], v[164:167], v[212:215], v[8:11]
	v_mfma_f32_16x16x32_bf16 v[52:55], v[168:171], v[184:187], v[52:55]
	v_mfma_f32_16x16x32_bf16 v[48:51], v[176:179], v[184:187], v[48:51]
	v_mfma_f32_16x16x32_bf16 v[36:39], v[168:171], v[192:195], v[36:39]
	v_mfma_f32_16x16x32_bf16 v[32:35], v[176:179], v[192:195], v[32:35]
	v_mfma_f32_16x16x32_bf16 v[20:23], v[168:171], v[200:203], v[20:23]
	v_mfma_f32_16x16x32_bf16 v[16:19], v[176:179], v[200:203], v[16:19]
	v_mfma_f32_16x16x32_bf16 v[4:7], v[168:171], v[208:211], v[4:7]
	v_mfma_f32_16x16x32_bf16 v[0:3], v[176:179], v[208:211], v[0:3]
	v_mfma_f32_16x16x32_bf16 v[52:55], v[172:175], v[188:191], v[52:55]
	v_mfma_f32_16x16x32_bf16 v[48:51], v[180:183], v[188:191], v[48:51]
	v_mfma_f32_16x16x32_bf16 v[36:39], v[172:175], v[196:199], v[36:39]
	v_mfma_f32_16x16x32_bf16 v[32:35], v[180:183], v[196:199], v[32:35]
	v_mfma_f32_16x16x32_bf16 v[20:23], v[172:175], v[204:207], v[20:23]
	v_mfma_f32_16x16x32_bf16 v[16:19], v[180:183], v[204:207], v[16:19]
	v_mfma_f32_16x16x32_bf16 v[4:7], v[172:175], v[212:215], v[4:7]
	v_mfma_f32_16x16x32_bf16 v[0:3], v[180:183], v[212:215], v[0:3]
	s_setprio 0
	s_barrier
	s_add_i32 s54, s54, 2
	s_add_u32 s24, s24, 0x100
	s_addc_u32 s25, s25, 0
	s_add_u32 s52, s52, 0x100
	s_addc_u32 s53, s53, 0
	s_cmp_gt_u32 s54, 13
	s_cbranch_scc0 .LBB0_337
	s_and_b64 vcc, exec, s[12:13]
	s_cbranch_vccz .LBB0_340
	s_barrier

; #define PG8_STAGE(bufoff, gbase, voff) do { _Pragma("unroll") for (int _i = 0; _i < 2; ++_i) \
;         __builtin_amdgcn_global_load_lds((const unsigned*)((const char*)(gbase) + (voff)[_i]), (PG8_LAS unsigned*)(lds + (bufoff) + ldsw + _i * 8192), 16, 0, 0); } while (0)
; #define PG8_LDA(dst, b, h) do { _Pragma("unroll") for (int m = 0; m < 4; ++m) _Pragma("unroll") for (int k = 0; k < 2; ++k) dst[m][k] = *(const PG8_LAS bf16x8*)(lds + PG8_SA(b, h) + aoff + m * 2048 + k * 1024); } while (0)
; #define PG8_LDB(dst, b, h) do { _Pragma("unroll") for (int n = 0; n < 2; ++n) _Pragma("unroll") for (int k = 0; k < 2; ++k) dst[n][k] = *(const PG8_LAS bf16x8*)(lds + PG8_SB(b, h) + boff + n * 2048 + k * 1024); } while (0)
; #define PG8_MMA(ai, bj, At, Bt) do { __builtin_amdgcn_s_setprio(1); _Pragma("unroll") for (int m = 0; m < 4; ++m) _Pragma("unroll") for (int n = 0; n < 2; ++n) _Pragma("unroll") for (int k = 0; k < 2; ++k) \
;         acc[ai][bj][m][n] = __builtin_amdgcn_mfma_f32_16x16x32_bf16(Bt[n][k], At[m][k], acc[ai][bj][m][n], 0, 0, 0); __builtin_amdgcn_s_setprio(0); } while (0)
; #define PG8_WAIT_V(n) asm volatile("s_waitcnt vmcnt(" #n ")" ::: "memory")
; #define PG8_WAIT_L(n) asm volatile("s_waitcnt lgkmcnt(" #n ")" ::: "memory")
; template <class Epi, class Sched, bool ALIGN_EPI = false, bool SP2 = false>
; __device__ __forceinline__ void gemm_phase(PG8_LAS unsigned char* lds, const Gemm g, const Sched& S, const Epi& E) {
;     ...
;             const bool last = (t == nt - 2);
;             const char* a1 = cA + (size_t)(t + 1) * kstep;
;             const char* a2 = last ? nA : cA + (size_t)(t + 2) * kstep; const char* b2 = last ? nB : cB + (size_t)(t + 2) * kstep;
;             const char* a3 = a2 + kstep; const char* b3 = b2 + kstep;
;             if (last && has_next) S.a_ready(nxt, ui + 1);
;             if constexpr (SP2) {
;             PG8_LDB(B0, 0, 0); PG8_LDB(B1, 0, 1); PG8_SCHED; PG8_LDA(At, 0, 0); PG8_STAGE(PG8_SA(1, 1), a1 + hstep, voffA);
;             PG8_WAIT_V(8); PG8_WAIT_L(0); PG8_BAR; PG8_MMA(0, 0, At, B0); PG8_MMA(0, 1, At, B1); PG8_BAR; PG8_SCHED;
;             PG8_LDA(At, 0, 1); PG8_STAGE(PG8_SB(0, 0), b2, voffB); PG8_STAGE(PG8_SB(0, 1), b2 + hstep, voffB); PG8_STAGE(PG8_SA(0, 0), a2, voffA);
;             PG8_WAIT_V(8); PG8_WAIT_L(0); PG8_BAR; PG8_MMA(1, 0, At, B0); PG8_MMA(1, 1, At, B1); PG8_BAR; PG8_SCHED;
.LBB0_418:
	ds_read_b128 v[120:123], v245
	ds_read_b128 v[128:131], v245 offset:1024
	ds_read_b128 v[136:139], v245 offset:2048
	ds_read_b128 v[140:143], v245 offset:3072
	ds_read_b128 v[144:147], v246
	ds_read_b128 v[148:151], v246 offset:1024
	ds_read_b128 v[152:155], v246 offset:2048
	ds_read_b128 v[156:159], v246 offset:3072
	s_add_u32 s26, s24, 0xfff50080
	s_addc_u32 s27, s25, -1
	s_cmp_eq_u32 s53, 40
	s_cselect_b32 s29, s7, s27
	s_cselect_b32 s28, s6, s26
	s_cselect_b32 s27, s23, s52
	s_cselect_b32 s26, s22, s51
	v_lshl_add_u64 v[204:205], s[24:25], 0, v[200:201]
	s_add_i32 m0, s35, 0xc000
	ds_read_b128 v[160:163], v247
	ds_read_b128 v[164:167], v247 offset:1024
	ds_read_b128 v[168:171], v247 offset:2048
	ds_read_b128 v[172:175], v247 offset:3072
	ds_read_b128 v[176:179], v247 offset:4096
	ds_read_b128 v[180:183], v247 offset:5120
	ds_read_b128 v[184:187], v247 offset:6144
	ds_read_b128 v[188:191], v247 offset:7168
	global_load_lds_dwordx4 v[204:205], off
	v_lshl_add_u64 v[204:205], s[24:25], 0, v[202:203]
	s_add_i32 m0, s35, 0xe000
	s_nop 0
	global_load_lds_dwordx4 v[204:205], off
	s_waitcnt vmcnt(8)
	s_waitcnt lgkmcnt(0)
	s_barrier
	s_setprio 1
	s_waitcnt lgkmcnt(0)
	v_mfma_f32_16x16x32_bf16 v[132:135], v[120:123], v[160:163], v[132:135]
	v_mfma_f32_16x16x32_bf16 v[124:127], v[136:139], v[160:163], v[124:127]
	v_mfma_f32_16x16x32_bf16 v[108:111], v[120:123], v[168:171], v[108:111]
	v_mfma_f32_16x16x32_bf16 v[104:107], v[136:139], v[168:171], v[104:107]
	v_mfma_f32_16x16x32_bf16 v[92:95], v[120:123], v[176:179], v[92:95]
	v_mfma_f32_16x16x32_bf16 v[88:91], v[136:139], v[176:179], v[88:91]
	v_mfma_f32_16x16x32_bf16 v[76:79], v[120:123], v[184:187], v[76:79]
	v_mfma_f32_16x16x32_bf16 v[72:75], v[136:139], v[184:187], v[72:75]
	v_mfma_f32_16x16x32_bf16 v[132:135], v[128:131], v[164:167], v[132:135]
	v_mfma_f32_16x16x32_bf16 v[124:127], v[140:143], v[164:167], v[124:127]
	v_mfma_f32_16x16x32_bf16 v[108:111], v[128:131], v[172:175], v[108:111]
	v_mfma_f32_16x16x32_bf16 v[104:107], v[140:143], v[172:175], v[104:107]
	v_mfma_f32_16x16x32_bf16 v[92:95], v[128:131], v[180:183], v[92:95]
	v_mfma_f32_16x16x32_bf16 v[88:91], v[140:143], v[180:183], v[88:91]
	v_mfma_f32_16x16x32_bf16 v[76:79], v[128:131], v[188:191], v[76:79]
	v_mfma_f32_16x16x32_bf16 v[72:75], v[140:143], v[188:191], v[72:75]
	v_mfma_f32_16x16x32_bf16 v[116:119], v[144:147], v[160:163], v[116:119]
	v_mfma_f32_16x16x32_bf16 v[112:115], v[152:155], v[160:163], v[112:115]
	v_mfma_f32_16x16x32_bf16 v[100:103], v[144:147], v[168:171], v[100:103]
	v_mfma_f32_16x16x32_bf16 v[96:99], v[152:155], v[168:171], v[96:99]
	v_mfma_f32_16x16x32_bf16 v[84:87], v[144:147], v[176:179], v[84:87]
	v_mfma_f32_16x16x32_bf16 v[80:83], v[152:155], v[176:179], v[80:83]
	v_mfma_f32_16x16x32_bf16 v[68:71], v[144:147], v[184:187], v[68:71]
	v_mfma_f32_16x16x32_bf16 v[64:67], v[152:155], v[184:187], v[64:67]
	v_mfma_f32_16x16x32_bf16 v[116:119], v[148:151], v[164:167], v[116:119]
	v_mfma_f32_16x16x32_bf16 v[112:115], v[156:159], v[164:167], v[112:115]
	v_mfma_f32_16x16x32_bf16 v[100:103], v[148:151], v[172:175], v[100:103]
	v_mfma_f32_16x16x32_bf16 v[96:99], v[156:159], v[172:175], v[96:99]
	v_mfma_f32_16x16x32_bf16 v[84:87], v[148:151], v[180:183], v[84:87]
	v_mfma_f32_16x16x32_bf16 v[80:83], v[156:159], v[180:183], v[80:83]
	v_mfma_f32_16x16x32_bf16 v[68:71], v[148:151], v[188:191], v[68:71]
	v_mfma_f32_16x16x32_bf16 v[64:67], v[156:159], v[188:191], v[64:67]
	s_setprio 0
	s_barrier
	s_add_i32 s54, s45, s34
	v_lshl_add_u64 v[204:205], s[26:27], 0, v[194:195]
	s_mov_b32 m0, s54
	ds_read_b128 v[160:163], v247 offset:16384
	ds_read_b128 v[164:167], v247 offset:17408
	ds_read_b128 v[168:171], v247 offset:18432
	ds_read_b128 v[172:175], v247 offset:19456
	ds_read_b128 v[176:179], v247 offset:20480
	ds_read_b128 v[180:183], v247 offset:21504
	ds_read_b128 v[184:187], v247 offset:22528
	ds_read_b128 v[188:191], v247 offset:23552
	global_load_lds_dwordx4 v[204:205], off
	s_add_i32 m0, s54, 0x2000
	s_add_u32 s54, s26, 0xb0000
	v_lshl_add_u64 v[206:207], s[26:27], 0, v[198:199]
	s_addc_u32 s55, s27, 0
	s_add_i32 s56, s46, s34
	global_load_lds_dwordx4 v[206:207], off
	v_lshl_add_u64 v[208:209], s[54:55], 0, v[194:195]
	s_mov_b32 m0, s56
	v_lshl_add_u64 v[210:211], s[28:29], 0, v[196:197]
	global_load_lds_dwordx4 v[208:209], off
	v_lshl_add_u64 v[208:209], s[54:55], 0, v[198:199]
	s_add_i32 m0, s56, 0x2000
	s_nop 0
	global_load_lds_dwordx4 v[208:209], off
	v_lshl_add_u64 v[208:209], s[28:29], 0, v[192:193]
	s_mov_b32 m0, s35
	s_nop 0
	global_load_lds_dwordx4 v[208:209], off
	s_mov_b32 m0, s36
	s_nop 0
	global_load_lds_dwordx4 v[210:211], off
	s_waitcnt vmcnt(8)
	s_waitcnt lgkmcnt(0)
	s_barrier
; #define PG8_STAGE(bufoff, gbase, voff) do { _Pragma("unroll") for (int _i = 0; _i < 2; ++_i) \
;         __builtin_amdgcn_global_load_lds((const unsigned*)((const char*)(gbase) + (voff)[_i]), (PG8_LAS unsigned*)(lds + (bufoff) + ldsw + _i * 8192), 16, 0, 0); } while (0)
; #define PG8_LDA(dst, b, h) do { _Pragma("unroll") for (int m = 0; m < 4; ++m) _Pragma("unroll") for (int k = 0; k < 2; ++k) dst[m][k] = *(const PG8_LAS bf16x8*)(lds + PG8_SA(b, h) + aoff + m * 2048 + k * 1024); } while (0)
; #define PG8_LDB(dst, b, h) do { _Pragma("unroll") for (int n = 0; n < 2; ++n) _Pragma("unroll") for (int k = 0; k < 2; ++k) dst[n][k] = *(const PG8_LAS bf16x8*)(lds + PG8_SB(b, h) + boff + n * 2048 + k * 1024); } while (0)
; #define PG8_MMA(ai, bj, At, Bt) do { __builtin_amdgcn_s_setprio(1); _Pragma("unroll") for (int m = 0; m < 4; ++m) _Pragma("unroll") for (int n = 0; n < 2; ++n) _Pragma("unroll") for (int k = 0; k < 2; ++k) \
;         acc[ai][bj][m][n] = __builtin_amdgcn_mfma_f32_16x16x32_bf16(Bt[n][k], At[m][k], acc[ai][bj][m][n], 0, 0, 0); __builtin_amdgcn_s_setprio(0); } while (0)
; #define PG8_WAIT_V(n) asm volatile("s_waitcnt vmcnt(" #n ")" ::: "memory")
; #define PG8_WAIT_L(n) asm volatile("s_waitcnt lgkmcnt(" #n ")" ::: "memory")
; #define PG8_BAR __builtin_amdgcn_s_barrier()
; #define PG8_SCHED __builtin_amdgcn_sched_barrier(0)
; template <class Epi, class Sched, bool ALIGN_EPI = false, bool SP2 = false>
; __device__ __forceinline__ void gemm_phase(PG8_LAS unsigned char* lds, const Gemm g, const Sched& S, const Epi& E) {
;     ...
;             PG8_WAIT_V(8); PG8_WAIT_L(0); PG8_BAR; PG8_MMA(1, 0, At, B0); PG8_MMA(1, 1, At, B1); PG8_BAR; PG8_SCHED;
;             PG8_LDB(B0, 1, 0); PG8_LDB(B1, 1, 1); PG8_SCHED; PG8_LDA(At, 1, 0); PG8_STAGE(PG8_SA(0, 1), a2 + hstep, voffA);
;             PG8_WAIT_V(8); PG8_WAIT_L(0); PG8_BAR; PG8_MMA(0, 0, At, B0); PG8_MMA(0, 1, At, B1); PG8_BAR; PG8_SCHED;
	s_setprio 1
	s_waitcnt lgkmcnt(0)
	v_mfma_f32_16x16x32_bf16 v[60:63], v[120:123], v[160:163], v[60:63]
	v_mfma_f32_16x16x32_bf16 v[56:59], v[136:139], v[160:163], v[56:59]
	v_mfma_f32_16x16x32_bf16 v[44:47], v[120:123], v[168:171], v[44:47]
	v_mfma_f32_16x16x32_bf16 v[40:43], v[136:139], v[168:171], v[40:43]
	v_mfma_f32_16x16x32_bf16 v[28:31], v[120:123], v[176:179], v[28:31]
	v_mfma_f32_16x16x32_bf16 v[24:27], v[136:139], v[176:179], v[24:27]
	v_mfma_f32_16x16x32_bf16 v[12:15], v[120:123], v[184:187], v[12:15]
	v_mfma_f32_16x16x32_bf16 v[8:11], v[136:139], v[184:187], v[8:11]
	v_mfma_f32_16x16x32_bf16 v[60:63], v[128:131], v[164:167], v[60:63]
	v_mfma_f32_16x16x32_bf16 v[56:59], v[140:143], v[164:167], v[56:59]
	v_mfma_f32_16x16x32_bf16 v[44:47], v[128:131], v[172:175], v[44:47]
	v_mfma_f32_16x16x32_bf16 v[40:43], v[140:143], v[172:175], v[40:43]
	v_mfma_f32_16x16x32_bf16 v[28:31], v[128:131], v[180:183], v[28:31]
	v_mfma_f32_16x16x32_bf16 v[24:27], v[140:143], v[180:183], v[24:27]
	v_mfma_f32_16x16x32_bf16 v[12:15], v[128:131], v[188:191], v[12:15]
	v_mfma_f32_16x16x32_bf16 v[8:11], v[140:143], v[188:191], v[8:11]
	v_mfma_f32_16x16x32_bf16 v[52:55], v[144:147], v[160:163], v[52:55]
	v_mfma_f32_16x16x32_bf16 v[48:51], v[152:155], v[160:163], v[48:51]
	v_mfma_f32_16x16x32_bf16 v[36:39], v[144:147], v[168:171], v[36:39]
	v_mfma_f32_16x16x32_bf16 v[32:35], v[152:155], v[168:171], v[32:35]
	v_mfma_f32_16x16x32_bf16 v[20:23], v[144:147], v[176:179], v[20:23]
	v_mfma_f32_16x16x32_bf16 v[16:19], v[152:155], v[176:179], v[16:19]
	v_mfma_f32_16x16x32_bf16 v[4:7], v[144:147], v[184:187], v[4:7]
	v_mfma_f32_16x16x32_bf16 v[0:3], v[152:155], v[184:187], v[0:3]
	v_mfma_f32_16x16x32_bf16 v[52:55], v[148:151], v[164:167], v[52:55]
	v_mfma_f32_16x16x32_bf16 v[48:51], v[156:159], v[164:167], v[48:51]
	v_mfma_f32_16x16x32_bf16 v[36:39], v[148:151], v[172:175], v[36:39]
	v_mfma_f32_16x16x32_bf16 v[32:35], v[156:159], v[172:175], v[32:35]
	v_mfma_f32_16x16x32_bf16 v[20:23], v[148:151], v[180:183], v[20:23]
	v_mfma_f32_16x16x32_bf16 v[16:19], v[156:159], v[180:183], v[16:19]
	v_mfma_f32_16x16x32_bf16 v[4:7], v[148:151], v[188:191], v[4:7]
	v_mfma_f32_16x16x32_bf16 v[0:3], v[156:159], v[188:191], v[0:3]
	s_setprio 0
	s_barrier
	s_add_i32 s54, 0, 0x18000
	s_add_i32 s55, 0, 0x1c000
	v_add_u32_e32 v140, s54, v243
	v_add_u32_e32 v156, s55, v243
	ds_read_b128 v[120:123], v140
	ds_read_b128 v[128:131], v140 offset:1024
	ds_read_b128 v[136:139], v140 offset:2048
	ds_read_b128 v[140:143], v140 offset:3072
	ds_read_b128 v[144:147], v156
	ds_read_b128 v[148:151], v156 offset:1024
	ds_read_b128 v[152:155], v156 offset:2048
	ds_read_b128 v[156:159], v156 offset:3072
	s_add_u32 s28, s28, 0xb0000
	s_addc_u32 s29, s29, 0
	s_mov_b32 m0, s37
	v_lshl_add_u64 v[212:213], s[28:29], 0, v[192:193]
	ds_read_b128 v[160:163], v247 offset:32768
	ds_read_b128 v[164:167], v247 offset:33792
	ds_read_b128 v[168:171], v247 offset:34816
	ds_read_b128 v[172:175], v247 offset:35840
	ds_read_b128 v[176:179], v247 offset:36864
	ds_read_b128 v[180:183], v247 offset:37888
	ds_read_b128 v[184:187], v247 offset:38912
	ds_read_b128 v[188:191], v247 offset:39936
	global_load_lds_dwordx4 v[212:213], off
	v_lshl_add_u64 v[212:213], s[28:29], 0, v[196:197]
	s_mov_b32 m0, s38
	s_nop 0
	global_load_lds_dwordx4 v[212:213], off
	s_waitcnt vmcnt(8)
	s_waitcnt lgkmcnt(0)
	s_barrier
	s_setprio 1
	s_waitcnt lgkmcnt(0)
	v_mfma_f32_16x16x32_bf16 v[132:135], v[120:123], v[160:163], v[132:135]
	v_mfma_f32_16x16x32_bf16 v[124:127], v[136:139], v[160:163], v[124:127]
	v_mfma_f32_16x16x32_bf16 v[108:111], v[120:123], v[168:171], v[108:111]
	v_mfma_f32_16x16x32_bf16 v[104:107], v[136:139], v[168:171], v[104:107]
	v_mfma_f32_16x16x32_bf16 v[92:95], v[120:123], v[176:179], v[92:95]
	v_mfma_f32_16x16x32_bf16 v[88:91], v[136:139], v[176:179], v[88:91]
	v_mfma_f32_16x16x32_bf16 v[76:79], v[120:123], v[184:187], v[76:79]
	v_mfma_f32_16x16x32_bf16 v[72:75], v[136:139], v[184:187], v[72:75]
	v_mfma_f32_16x16x32_bf16 v[132:135], v[128:131], v[164:167], v[132:135]
	v_mfma_f32_16x16x32_bf16 v[124:127], v[140:143], v[164:167], v[124:127]
	v_mfma_f32_16x16x32_bf16 v[108:111], v[128:131], v[172:175], v[108:111]
	v_mfma_f32_16x16x32_bf16 v[104:107], v[140:143], v[172:175], v[104:107]
	v_mfma_f32_16x16x32_bf16 v[92:95], v[128:131], v[180:183], v[92:95]
	v_mfma_f32_16x16x32_bf16 v[88:91], v[140:143], v[180:183], v[88:91]
	v_mfma_f32_16x16x32_bf16 v[76:79], v[128:131], v[188:191], v[76:79]
	v_mfma_f32_16x16x32_bf16 v[72:75], v[140:143], v[188:191], v[72:75]
	v_mfma_f32_16x16x32_bf16 v[116:119], v[144:147], v[160:163], v[116:119]
	v_mfma_f32_16x16x32_bf16 v[112:115], v[152:155], v[160:163], v[112:115]
	v_mfma_f32_16x16x32_bf16 v[100:103], v[144:147], v[168:171], v[100:103]
	v_mfma_f32_16x16x32_bf16 v[96:99], v[152:155], v[168:171], v[96:99]
	v_mfma_f32_16x16x32_bf16 v[84:87], v[144:147], v[176:179], v[84:87]
	v_mfma_f32_16x16x32_bf16 v[80:83], v[152:155], v[176:179], v[80:83]
	v_mfma_f32_16x16x32_bf16 v[68:71], v[144:147], v[184:187], v[68:71]
	v_mfma_f32_16x16x32_bf16 v[64:67], v[152:155], v[184:187], v[64:67]
	v_mfma_f32_16x16x32_bf16 v[116:119], v[148:151], v[164:167], v[116:119]
	v_mfma_f32_16x16x32_bf16 v[112:115], v[156:159], v[164:167], v[112:115]
	v_mfma_f32_16x16x32_bf16 v[100:103], v[148:151], v[172:175], v[100:103]
	v_mfma_f32_16x16x32_bf16 v[96:99], v[156:159], v[172:175], v[96:99]
	v_mfma_f32_16x16x32_bf16 v[84:87], v[148:151], v[180:183], v[84:87]
	v_mfma_f32_16x16x32_bf16 v[80:83], v[156:159], v[180:183], v[80:83]
	v_mfma_f32_16x16x32_bf16 v[68:71], v[148:151], v[188:191], v[68:71]
	v_mfma_f32_16x16x32_bf16 v[64:67], v[156:159], v[188:191], v[64:67]
	s_setprio 0
	s_barrier
; #define PG8_STAGE(bufoff, gbase, voff) do { _Pragma("unroll") for (int _i = 0; _i < 2; ++_i) \
;         __builtin_amdgcn_global_load_lds((const unsigned*)((const char*)(gbase) + (voff)[_i]), (PG8_LAS unsigned*)(lds + (bufoff) + ldsw + _i * 8192), 16, 0, 0); } while (0)
; #define PG8_LDA(dst, b, h) do { _Pragma("unroll") for (int m = 0; m < 4; ++m) _Pragma("unroll") for (int k = 0; k < 2; ++k) dst[m][k] = *(const PG8_LAS bf16x8*)(lds + PG8_SA(b, h) + aoff + m * 2048 + k * 1024); } while (0)
; #define PG8_MMA(ai, bj, At, Bt) do { __builtin_amdgcn_s_setprio(1); _Pragma("unroll") for (int m = 0; m < 4; ++m) _Pragma("unroll") for (int n = 0; n < 2; ++n) _Pragma("unroll") for (int k = 0; k < 2; ++k) \
;         acc[ai][bj][m][n] = __builtin_amdgcn_mfma_f32_16x16x32_bf16(Bt[n][k], At[m][k], acc[ai][bj][m][n], 0, 0, 0); __builtin_amdgcn_s_setprio(0); } while (0)
; #define PG8_WAIT_V(n) asm volatile("s_waitcnt vmcnt(" #n ")" ::: "memory")
; #define PG8_WAIT_L(n) asm volatile("s_waitcnt lgkmcnt(" #n ")" ::: "memory")
; #define PG8_BAR __builtin_amdgcn_s_barrier()
; #define PG8_SCHED __builtin_amdgcn_sched_barrier(0)
; template <class Epi, class Sched, bool ALIGN_EPI = false, bool SP2 = false>
; __device__ __forceinline__ void gemm_phase(PG8_LAS unsigned char* lds, const Gemm g, const Sched& S, const Epi& E) {
;     ...
;             PG8_LDA(At, 1, 1); PG8_STAGE(PG8_SB(1, 0), b3, voffB); PG8_STAGE(PG8_SB(1, 1), b3 + hstep, voffB); PG8_STAGE(PG8_SA(1, 0), a3, voffA);
;             PG8_WAIT_V(8); PG8_WAIT_L(0); PG8_BAR; PG8_MMA(1, 0, At, B0); PG8_MMA(1, 1, At, B1); PG8_BAR; PG8_SCHED;
;     ...
;         if constexpr (ALIGN_EPI) { if (wr == 0) PG8_BAR; }
;         if constexpr (!Epi::AFTER_DRAIN) { E(acc, cur, wr, wc, fr, fq, ui); S.done(cur); }
;         if (!has_next) break;
	s_add_i32 s28, s54, s34
	v_lshl_add_u64 v[204:205], v[204:205], 0, s[18:19]
	s_mov_b32 m0, s28
	ds_read_b128 v[160:163], v247 offset:49152
	ds_read_b128 v[164:167], v247 offset:50176
	ds_read_b128 v[168:171], v247 offset:51200
	ds_read_b128 v[172:175], v247 offset:52224
	ds_read_b128 v[176:179], v247 offset:53248
	ds_read_b128 v[180:183], v247 offset:54272
	ds_read_b128 v[184:187], v247 offset:55296
	ds_read_b128 v[188:191], v247 offset:56320
	global_load_lds_dwordx4 v[204:205], off
	s_add_i32 m0, s28, 0x2000
	s_add_u32 s26, s26, 0xb0080
	v_lshl_add_u64 v[204:205], v[206:207], 0, s[18:19]
	s_addc_u32 s27, s27, 0
	s_add_i32 s28, s55, s34
	global_load_lds_dwordx4 v[204:205], off
	v_lshl_add_u64 v[204:205], s[26:27], 0, v[194:195]
	s_mov_b32 m0, s28
	s_nop 0
	global_load_lds_dwordx4 v[204:205], off
	v_lshl_add_u64 v[204:205], s[26:27], 0, v[198:199]
	s_add_i32 m0, s28, 0x2000
	s_nop 0
	global_load_lds_dwordx4 v[204:205], off
	v_lshl_add_u64 v[204:205], v[208:209], 0, s[18:19]
	s_mov_b32 m0, s40
	s_nop 0
	global_load_lds_dwordx4 v[204:205], off
	v_lshl_add_u64 v[204:205], v[210:211], 0, s[18:19]
	s_mov_b32 m0, s41
	s_nop 0
	global_load_lds_dwordx4 v[204:205], off
	s_waitcnt vmcnt(8)
	s_waitcnt lgkmcnt(0)
	s_barrier
	s_setprio 1
	s_waitcnt lgkmcnt(0)
	v_mfma_f32_16x16x32_bf16 v[60:63], v[120:123], v[160:163], v[60:63]
	v_mfma_f32_16x16x32_bf16 v[56:59], v[136:139], v[160:163], v[56:59]
	v_mfma_f32_16x16x32_bf16 v[44:47], v[120:123], v[168:171], v[44:47]
	v_mfma_f32_16x16x32_bf16 v[40:43], v[136:139], v[168:171], v[40:43]
	v_mfma_f32_16x16x32_bf16 v[28:31], v[120:123], v[176:179], v[28:31]
	v_mfma_f32_16x16x32_bf16 v[24:27], v[136:139], v[176:179], v[24:27]
	v_mfma_f32_16x16x32_bf16 v[12:15], v[120:123], v[184:187], v[12:15]
	v_mfma_f32_16x16x32_bf16 v[8:11], v[136:139], v[184:187], v[8:11]
	v_mfma_f32_16x16x32_bf16 v[60:63], v[128:131], v[164:167], v[60:63]
	v_mfma_f32_16x16x32_bf16 v[56:59], v[140:143], v[164:167], v[56:59]
	v_mfma_f32_16x16x32_bf16 v[44:47], v[128:131], v[172:175], v[44:47]
	v_mfma_f32_16x16x32_bf16 v[40:43], v[140:143], v[172:175], v[40:43]
	v_mfma_f32_16x16x32_bf16 v[28:31], v[128:131], v[180:183], v[28:31]
	v_mfma_f32_16x16x32_bf16 v[24:27], v[140:143], v[180:183], v[24:27]
	v_mfma_f32_16x16x32_bf16 v[12:15], v[128:131], v[188:191], v[12:15]
	v_mfma_f32_16x16x32_bf16 v[8:11], v[140:143], v[188:191], v[8:11]
	v_mfma_f32_16x16x32_bf16 v[52:55], v[144:147], v[160:163], v[52:55]
	v_mfma_f32_16x16x32_bf16 v[48:51], v[152:155], v[160:163], v[48:51]
	v_mfma_f32_16x16x32_bf16 v[36:39], v[144:147], v[168:171], v[36:39]
	v_mfma_f32_16x16x32_bf16 v[32:35], v[152:155], v[168:171], v[32:35]
	v_mfma_f32_16x16x32_bf16 v[20:23], v[144:147], v[176:179], v[20:23]
	v_mfma_f32_16x16x32_bf16 v[16:19], v[152:155], v[176:179], v[16:19]
	v_mfma_f32_16x16x32_bf16 v[4:7], v[144:147], v[184:187], v[4:7]
	v_mfma_f32_16x16x32_bf16 v[0:3], v[152:155], v[184:187], v[0:3]
	v_mfma_f32_16x16x32_bf16 v[52:55], v[148:151], v[164:167], v[52:55]
	v_mfma_f32_16x16x32_bf16 v[48:51], v[156:159], v[164:167], v[48:51]
	v_mfma_f32_16x16x32_bf16 v[36:39], v[148:151], v[172:175], v[36:39]
	v_mfma_f32_16x16x32_bf16 v[32:35], v[156:159], v[172:175], v[32:35]
	v_mfma_f32_16x16x32_bf16 v[20:23], v[148:151], v[180:183], v[20:23]
	v_mfma_f32_16x16x32_bf16 v[16:19], v[156:159], v[180:183], v[16:19]
	v_mfma_f32_16x16x32_bf16 v[4:7], v[148:151], v[188:191], v[4:7]
	v_mfma_f32_16x16x32_bf16 v[0:3], v[156:159], v[188:191], v[0:3]
	s_setprio 0
	s_barrier
	s_add_i32 s53, s53, 2
	s_add_u32 s24, s24, 0x100
	s_addc_u32 s25, s25, 0
	s_add_u32 s51, s51, 0x100
	s_addc_u32 s52, s52, 0
	s_cmp_gt_u32 s53, 41
	s_cbranch_scc0 .LBB0_418
	s_and_b64 vcc, exec, s[20:21]
	s_cbranch_vccz .LBB0_421
	s_barrier

; #define PG8_STAGE(bufoff, gbase, voff) do { _Pragma("unroll") for (int _i = 0; _i < 2; ++_i) \
;         __builtin_amdgcn_global_load_lds((const unsigned*)((const char*)(gbase) + (voff)[_i]), (PG8_LAS unsigned*)(lds + (bufoff) + ldsw + _i * 8192), 16, 0, 0); } while (0)
; #define PG8_LDA(dst, b, h) do { _Pragma("unroll") for (int m = 0; m < 4; ++m) _Pragma("unroll") for (int k = 0; k < 2; ++k) dst[m][k] = *(const PG8_LAS bf16x8*)(lds + PG8_SA(b, h) + aoff + m * 2048 + k * 1024); } while (0)
; #define PG8_LDB(dst, b, h) do { _Pragma("unroll") for (int n = 0; n < 2; ++n) _Pragma("unroll") for (int k = 0; k < 2; ++k) dst[n][k] = *(const PG8_LAS bf16x8*)(lds + PG8_SB(b, h) + boff + n * 2048 + k * 1024); } while (0)
; #define PG8_MMA(ai, bj, At, Bt) do { __builtin_amdgcn_s_setprio(1); _Pragma("unroll") for (int m = 0; m < 4; ++m) _Pragma("unroll") for (int n = 0; n < 2; ++n) _Pragma("unroll") for (int k = 0; k < 2; ++k) \
;         acc[ai][bj][m][n] = __builtin_amdgcn_mfma_f32_16x16x32_bf16(Bt[n][k], At[m][k], acc[ai][bj][m][n], 0, 0, 0); __builtin_amdgcn_s_setprio(0); } while (0)
; #define PG8_WAIT_V(n) asm volatile("s_waitcnt vmcnt(" #n ")" ::: "memory")
; #define PG8_WAIT_L(n) asm volatile("s_waitcnt lgkmcnt(" #n ")" ::: "memory")
; template <class Epi, class Sched, bool ALIGN_EPI = false, bool SP2 = false>
; __device__ __forceinline__ void gemm_phase(PG8_LAS unsigned char* lds, const Gemm g, const Sched& S, const Epi& E) {
;     ...
;             const bool last = (t == nt - 2);
;             const char* a1 = cA + (size_t)(t + 1) * kstep;
;             const char* a2 = last ? nA : cA + (size_t)(t + 2) * kstep; const char* b2 = last ? nB : cB + (size_t)(t + 2) * kstep;
;             const char* a3 = a2 + kstep; const char* b3 = b2 + kstep;
;             if (last && has_next) S.a_ready(nxt, ui + 1);
;             if constexpr (SP2) {
;             PG8_LDB(B0, 0, 0); PG8_LDB(B1, 0, 1); PG8_SCHED; PG8_LDA(At, 0, 0); PG8_STAGE(PG8_SA(1, 1), a1 + hstep, voffA);
;             PG8_WAIT_V(8); PG8_WAIT_L(0); PG8_BAR; PG8_MMA(0, 0, At, B0); PG8_MMA(0, 1, At, B1); PG8_BAR; PG8_SCHED;
;             PG8_LDA(At, 0, 1); PG8_STAGE(PG8_SB(0, 0), b2, voffB); PG8_STAGE(PG8_SB(0, 1), b2 + hstep, voffB); PG8_STAGE(PG8_SA(0, 0), a2, voffA);
;             PG8_WAIT_V(8); PG8_WAIT_L(0); PG8_BAR; PG8_MMA(1, 0, At, B0); PG8_MMA(1, 1, At, B1); PG8_BAR; PG8_SCHED;
.LBB0_509:
	ds_read_b128 v[148:151], v162
	ds_read_b128 v[166:169], v162 offset:1024
	ds_read_b128 v[170:173], v162 offset:2048
	ds_read_b128 v[174:177], v162 offset:3072
	ds_read_b128 v[178:181], v163
	ds_read_b128 v[182:185], v163 offset:1024
	ds_read_b128 v[186:189], v163 offset:2048
	ds_read_b128 v[190:193], v163 offset:3072
	s_add_u32 s40, s38, 0xfffc0080
	s_addc_u32 s41, s39, -1
	s_cmp_eq_u32 s70, 12
	s_cselect_b32 s43, s9, s41
	s_cselect_b32 s42, s14, s40
	s_cselect_b32 s41, s29, s45
	s_cselect_b32 s40, s31, s44
	v_lshl_add_u64 v[226:227], s[38:39], 0, v[132:133]
	s_add_i32 m0, s52, 0xc000
	ds_read_b128 v[194:197], v164
	ds_read_b128 v[198:201], v164 offset:1024
	ds_read_b128 v[202:205], v164 offset:2048
	ds_read_b128 v[206:209], v164 offset:3072
	ds_read_b128 v[210:213], v164 offset:4096
	ds_read_b128 v[214:217], v164 offset:5120
	ds_read_b128 v[218:221], v164 offset:6144
	ds_read_b128 v[222:225], v164 offset:7168
	global_load_lds_dwordx4 v[226:227], off
	v_lshl_add_u64 v[226:227], s[38:39], 0, v[134:135]
	s_add_i32 m0, s52, 0xe000
	s_nop 0
	global_load_lds_dwordx4 v[226:227], off
	s_waitcnt vmcnt(8)
	s_waitcnt lgkmcnt(0)
	s_barrier
	s_setprio 1
	s_waitcnt lgkmcnt(0)
	v_mfma_f32_16x16x32_bf16 v[124:127], v[148:151], v[194:197], v[124:127]
	v_mfma_f32_16x16x32_bf16 v[120:123], v[170:173], v[194:197], v[120:123]
	v_mfma_f32_16x16x32_bf16 v[108:111], v[148:151], v[202:205], v[108:111]
	v_mfma_f32_16x16x32_bf16 v[104:107], v[170:173], v[202:205], v[104:107]
	v_mfma_f32_16x16x32_bf16 v[92:95], v[148:151], v[210:213], v[92:95]
	v_mfma_f32_16x16x32_bf16 v[88:91], v[170:173], v[210:213], v[88:91]
	v_mfma_f32_16x16x32_bf16 v[76:79], v[148:151], v[218:221], v[76:79]
	v_mfma_f32_16x16x32_bf16 v[72:75], v[170:173], v[218:221], v[72:75]
	v_mfma_f32_16x16x32_bf16 v[124:127], v[166:169], v[198:201], v[124:127]
	v_mfma_f32_16x16x32_bf16 v[120:123], v[174:177], v[198:201], v[120:123]
	v_mfma_f32_16x16x32_bf16 v[108:111], v[166:169], v[206:209], v[108:111]
	v_mfma_f32_16x16x32_bf16 v[104:107], v[174:177], v[206:209], v[104:107]
	v_mfma_f32_16x16x32_bf16 v[92:95], v[166:169], v[214:217], v[92:95]
	v_mfma_f32_16x16x32_bf16 v[88:91], v[174:177], v[214:217], v[88:91]
	v_mfma_f32_16x16x32_bf16 v[76:79], v[166:169], v[222:225], v[76:79]
	v_mfma_f32_16x16x32_bf16 v[72:75], v[174:177], v[222:225], v[72:75]
	v_mfma_f32_16x16x32_bf16 v[116:119], v[178:181], v[194:197], v[116:119]
	v_mfma_f32_16x16x32_bf16 v[112:115], v[186:189], v[194:197], v[112:115]
	v_mfma_f32_16x16x32_bf16 v[100:103], v[178:181], v[202:205], v[100:103]
	v_mfma_f32_16x16x32_bf16 v[96:99], v[186:189], v[202:205], v[96:99]
	v_mfma_f32_16x16x32_bf16 v[84:87], v[178:181], v[210:213], v[84:87]
	v_mfma_f32_16x16x32_bf16 v[80:83], v[186:189], v[210:213], v[80:83]
	v_mfma_f32_16x16x32_bf16 v[68:71], v[178:181], v[218:221], v[68:71]
	v_mfma_f32_16x16x32_bf16 v[64:67], v[186:189], v[218:221], v[64:67]
	v_mfma_f32_16x16x32_bf16 v[116:119], v[182:185], v[198:201], v[116:119]
	v_mfma_f32_16x16x32_bf16 v[112:115], v[190:193], v[198:201], v[112:115]
	v_mfma_f32_16x16x32_bf16 v[100:103], v[182:185], v[206:209], v[100:103]
	v_mfma_f32_16x16x32_bf16 v[96:99], v[190:193], v[206:209], v[96:99]
	v_mfma_f32_16x16x32_bf16 v[84:87], v[182:185], v[214:217], v[84:87]
	v_mfma_f32_16x16x32_bf16 v[80:83], v[190:193], v[214:217], v[80:83]
	v_mfma_f32_16x16x32_bf16 v[68:71], v[182:185], v[222:225], v[68:71]
	v_mfma_f32_16x16x32_bf16 v[64:67], v[190:193], v[222:225], v[64:67]
	s_setprio 0
	s_barrier
	s_add_i32 s71, s61, s33
	v_lshl_add_u64 v[226:227], s[40:41], 0, v[138:139]
	s_mov_b32 m0, s71
	ds_read_b128 v[194:197], v164 offset:16384
	ds_read_b128 v[198:201], v164 offset:17408
	ds_read_b128 v[202:205], v164 offset:18432
	ds_read_b128 v[206:209], v164 offset:19456
	ds_read_b128 v[210:213], v164 offset:20480
	ds_read_b128 v[214:217], v164 offset:21504
	ds_read_b128 v[218:221], v164 offset:22528
	ds_read_b128 v[222:225], v164 offset:23552
	global_load_lds_dwordx4 v[226:227], off
	s_add_i32 m0, s71, 0x2000
	s_add_u32 s72, s40, 0x40000
	v_lshl_add_u64 v[228:229], s[40:41], 0, v[142:143]
	s_addc_u32 s73, s41, 0
	s_add_i32 s71, s62, s33
	global_load_lds_dwordx4 v[228:229], off
	v_lshl_add_u64 v[230:231], s[72:73], 0, v[138:139]
	s_mov_b32 m0, s71
	v_lshl_add_u64 v[232:233], s[42:43], 0, v[140:141]
	global_load_lds_dwordx4 v[230:231], off
	v_lshl_add_u64 v[230:231], s[72:73], 0, v[142:143]
	s_add_i32 m0, s71, 0x2000
	s_nop 0
	global_load_lds_dwordx4 v[230:231], off
	v_lshl_add_u64 v[230:231], s[42:43], 0, v[136:137]
	s_mov_b32 m0, s52
	s_nop 0
	global_load_lds_dwordx4 v[230:231], off
	s_mov_b32 m0, s53
	s_nop 0
	global_load_lds_dwordx4 v[232:233], off
	s_waitcnt vmcnt(8)
	s_waitcnt lgkmcnt(0)
	s_barrier
; #define PG8_STAGE(bufoff, gbase, voff) do { _Pragma("unroll") for (int _i = 0; _i < 2; ++_i) \
;         __builtin_amdgcn_global_load_lds((const unsigned*)((const char*)(gbase) + (voff)[_i]), (PG8_LAS unsigned*)(lds + (bufoff) + ldsw + _i * 8192), 16, 0, 0); } while (0)
; #define PG8_LDA(dst, b, h) do { _Pragma("unroll") for (int m = 0; m < 4; ++m) _Pragma("unroll") for (int k = 0; k < 2; ++k) dst[m][k] = *(const PG8_LAS bf16x8*)(lds + PG8_SA(b, h) + aoff + m * 2048 + k * 1024); } while (0)
; #define PG8_LDB(dst, b, h) do { _Pragma("unroll") for (int n = 0; n < 2; ++n) _Pragma("unroll") for (int k = 0; k < 2; ++k) dst[n][k] = *(const PG8_LAS bf16x8*)(lds + PG8_SB(b, h) + boff + n * 2048 + k * 1024); } while (0)
; #define PG8_MMA(ai, bj, At, Bt) do { __builtin_amdgcn_s_setprio(1); _Pragma("unroll") for (int m = 0; m < 4; ++m) _Pragma("unroll") for (int n = 0; n < 2; ++n) _Pragma("unroll") for (int k = 0; k < 2; ++k) \
;         acc[ai][bj][m][n] = __builtin_amdgcn_mfma_f32_16x16x32_bf16(Bt[n][k], At[m][k], acc[ai][bj][m][n], 0, 0, 0); __builtin_amdgcn_s_setprio(0); } while (0)
; #define PG8_WAIT_V(n) asm volatile("s_waitcnt vmcnt(" #n ")" ::: "memory")
; #define PG8_WAIT_L(n) asm volatile("s_waitcnt lgkmcnt(" #n ")" ::: "memory")
; #define PG8_BAR __builtin_amdgcn_s_barrier()
; #define PG8_SCHED __builtin_amdgcn_sched_barrier(0)
; template <class Epi, class Sched, bool ALIGN_EPI = false, bool SP2 = false>
; __device__ __forceinline__ void gemm_phase(PG8_LAS unsigned char* lds, const Gemm g, const Sched& S, const Epi& E) {
;     ...
;             PG8_WAIT_V(8); PG8_WAIT_L(0); PG8_BAR; PG8_MMA(1, 0, At, B0); PG8_MMA(1, 1, At, B1); PG8_BAR; PG8_SCHED;
;             PG8_LDB(B0, 1, 0); PG8_LDB(B1, 1, 1); PG8_SCHED; PG8_LDA(At, 1, 0); PG8_STAGE(PG8_SA(0, 1), a2 + hstep, voffA);
;             PG8_WAIT_V(8); PG8_WAIT_L(0); PG8_BAR; PG8_MMA(0, 0, At, B0); PG8_MMA(0, 1, At, B1); PG8_BAR; PG8_SCHED;
	s_setprio 1
	s_waitcnt lgkmcnt(0)
	v_mfma_f32_16x16x32_bf16 v[60:63], v[148:151], v[194:197], v[60:63]
	v_mfma_f32_16x16x32_bf16 v[56:59], v[170:173], v[194:197], v[56:59]
	v_mfma_f32_16x16x32_bf16 v[44:47], v[148:151], v[202:205], v[44:47]
	v_mfma_f32_16x16x32_bf16 v[40:43], v[170:173], v[202:205], v[40:43]
	v_mfma_f32_16x16x32_bf16 v[28:31], v[148:151], v[210:213], v[28:31]
	v_mfma_f32_16x16x32_bf16 v[24:27], v[170:173], v[210:213], v[24:27]
	v_mfma_f32_16x16x32_bf16 v[12:15], v[148:151], v[218:221], v[12:15]
	v_mfma_f32_16x16x32_bf16 v[8:11], v[170:173], v[218:221], v[8:11]
	v_mfma_f32_16x16x32_bf16 v[60:63], v[166:169], v[198:201], v[60:63]
	v_mfma_f32_16x16x32_bf16 v[56:59], v[174:177], v[198:201], v[56:59]
	v_mfma_f32_16x16x32_bf16 v[44:47], v[166:169], v[206:209], v[44:47]
	v_mfma_f32_16x16x32_bf16 v[40:43], v[174:177], v[206:209], v[40:43]
	v_mfma_f32_16x16x32_bf16 v[28:31], v[166:169], v[214:217], v[28:31]
	v_mfma_f32_16x16x32_bf16 v[24:27], v[174:177], v[214:217], v[24:27]
	v_mfma_f32_16x16x32_bf16 v[12:15], v[166:169], v[222:225], v[12:15]
	v_mfma_f32_16x16x32_bf16 v[8:11], v[174:177], v[222:225], v[8:11]
	v_mfma_f32_16x16x32_bf16 v[52:55], v[178:181], v[194:197], v[52:55]
	v_mfma_f32_16x16x32_bf16 v[48:51], v[186:189], v[194:197], v[48:51]
	v_mfma_f32_16x16x32_bf16 v[36:39], v[178:181], v[202:205], v[36:39]
	v_mfma_f32_16x16x32_bf16 v[32:35], v[186:189], v[202:205], v[32:35]
	v_mfma_f32_16x16x32_bf16 v[20:23], v[178:181], v[210:213], v[20:23]
	v_mfma_f32_16x16x32_bf16 v[16:19], v[186:189], v[210:213], v[16:19]
	v_mfma_f32_16x16x32_bf16 v[4:7], v[178:181], v[218:221], v[4:7]
	v_mfma_f32_16x16x32_bf16 v[0:3], v[186:189], v[218:221], v[0:3]
	v_mfma_f32_16x16x32_bf16 v[52:55], v[182:185], v[198:201], v[52:55]
	v_mfma_f32_16x16x32_bf16 v[48:51], v[190:193], v[198:201], v[48:51]
	v_mfma_f32_16x16x32_bf16 v[36:39], v[182:185], v[206:209], v[36:39]
	v_mfma_f32_16x16x32_bf16 v[32:35], v[190:193], v[206:209], v[32:35]
	v_mfma_f32_16x16x32_bf16 v[20:23], v[182:185], v[214:217], v[20:23]
	v_mfma_f32_16x16x32_bf16 v[16:19], v[190:193], v[214:217], v[16:19]
	v_mfma_f32_16x16x32_bf16 v[4:7], v[182:185], v[222:225], v[4:7]
	v_mfma_f32_16x16x32_bf16 v[0:3], v[190:193], v[222:225], v[0:3]
	s_setprio 0
	s_barrier
	s_add_i32 s71, 0, 0x18000
	v_add_u32_e32 v130, s71, v160
	s_add_i32 s72, 0, 0x1c000
	ds_read_b128 v[148:151], v130
	ds_read_b128 v[166:169], v130 offset:1024
	ds_read_b128 v[170:173], v130 offset:2048
	ds_read_b128 v[174:177], v130 offset:3072
	v_add_u32_e32 v130, s72, v160
	ds_read_b128 v[178:181], v130
	ds_read_b128 v[182:185], v130 offset:1024
	ds_read_b128 v[186:189], v130 offset:2048
	ds_read_b128 v[190:193], v130 offset:3072
	s_add_u32 s42, s42, 0x40000
	s_addc_u32 s43, s43, 0
	s_mov_b32 m0, s54
	v_lshl_add_u64 v[234:235], s[42:43], 0, v[136:137]
	ds_read_b128 v[194:197], v164 offset:32768
	ds_read_b128 v[198:201], v164 offset:33792
	ds_read_b128 v[202:205], v164 offset:34816
	ds_read_b128 v[206:209], v164 offset:35840
	ds_read_b128 v[210:213], v164 offset:36864
	ds_read_b128 v[214:217], v164 offset:37888
	ds_read_b128 v[218:221], v164 offset:38912
	ds_read_b128 v[222:225], v164 offset:39936
	global_load_lds_dwordx4 v[234:235], off
	v_lshl_add_u64 v[234:235], s[42:43], 0, v[140:141]
	s_mov_b32 m0, s55
	s_nop 0
	global_load_lds_dwordx4 v[234:235], off
	s_waitcnt vmcnt(8)
	s_waitcnt lgkmcnt(0)
	s_barrier
	s_setprio 1
	s_waitcnt lgkmcnt(0)
	v_mfma_f32_16x16x32_bf16 v[124:127], v[148:151], v[194:197], v[124:127]
	v_mfma_f32_16x16x32_bf16 v[120:123], v[170:173], v[194:197], v[120:123]
	v_mfma_f32_16x16x32_bf16 v[108:111], v[148:151], v[202:205], v[108:111]
	v_mfma_f32_16x16x32_bf16 v[104:107], v[170:173], v[202:205], v[104:107]
	v_mfma_f32_16x16x32_bf16 v[92:95], v[148:151], v[210:213], v[92:95]
	v_mfma_f32_16x16x32_bf16 v[88:91], v[170:173], v[210:213], v[88:91]
	v_mfma_f32_16x16x32_bf16 v[76:79], v[148:151], v[218:221], v[76:79]
	v_mfma_f32_16x16x32_bf16 v[72:75], v[170:173], v[218:221], v[72:75]
	v_mfma_f32_16x16x32_bf16 v[124:127], v[166:169], v[198:201], v[124:127]
	v_mfma_f32_16x16x32_bf16 v[120:123], v[174:177], v[198:201], v[120:123]
	v_mfma_f32_16x16x32_bf16 v[108:111], v[166:169], v[206:209], v[108:111]
	v_mfma_f32_16x16x32_bf16 v[104:107], v[174:177], v[206:209], v[104:107]
	v_mfma_f32_16x16x32_bf16 v[92:95], v[166:169], v[214:217], v[92:95]
	v_mfma_f32_16x16x32_bf16 v[88:91], v[174:177], v[214:217], v[88:91]
	v_mfma_f32_16x16x32_bf16 v[76:79], v[166:169], v[222:225], v[76:79]
	v_mfma_f32_16x16x32_bf16 v[72:75], v[174:177], v[222:225], v[72:75]
	v_mfma_f32_16x16x32_bf16 v[116:119], v[178:181], v[194:197], v[116:119]
	v_mfma_f32_16x16x32_bf16 v[112:115], v[186:189], v[194:197], v[112:115]
	v_mfma_f32_16x16x32_bf16 v[100:103], v[178:181], v[202:205], v[100:103]
	v_mfma_f32_16x16x32_bf16 v[96:99], v[186:189], v[202:205], v[96:99]
	v_mfma_f32_16x16x32_bf16 v[84:87], v[178:181], v[210:213], v[84:87]
	v_mfma_f32_16x16x32_bf16 v[80:83], v[186:189], v[210:213], v[80:83]
	v_mfma_f32_16x16x32_bf16 v[68:71], v[178:181], v[218:221], v[68:71]
	v_mfma_f32_16x16x32_bf16 v[64:67], v[186:189], v[218:221], v[64:67]
	v_mfma_f32_16x16x32_bf16 v[116:119], v[182:185], v[198:201], v[116:119]
	v_mfma_f32_16x16x32_bf16 v[112:115], v[190:193], v[198:201], v[112:115]
	v_mfma_f32_16x16x32_bf16 v[100:103], v[182:185], v[206:209], v[100:103]
	v_mfma_f32_16x16x32_bf16 v[96:99], v[190:193], v[206:209], v[96:99]
	v_mfma_f32_16x16x32_bf16 v[84:87], v[182:185], v[214:217], v[84:87]
	v_mfma_f32_16x16x32_bf16 v[80:83], v[190:193], v[214:217], v[80:83]
	v_mfma_f32_16x16x32_bf16 v[68:71], v[182:185], v[222:225], v[68:71]
	v_mfma_f32_16x16x32_bf16 v[64:67], v[190:193], v[222:225], v[64:67]
	s_setprio 0
	s_barrier
; #define PG8_STAGE(bufoff, gbase, voff) do { _Pragma("unroll") for (int _i = 0; _i < 2; ++_i) \
;         __builtin_amdgcn_global_load_lds((const unsigned*)((const char*)(gbase) + (voff)[_i]), (PG8_LAS unsigned*)(lds + (bufoff) + ldsw + _i * 8192), 16, 0, 0); } while (0)
; #define PG8_LDA(dst, b, h) do { _Pragma("unroll") for (int m = 0; m < 4; ++m) _Pragma("unroll") for (int k = 0; k < 2; ++k) dst[m][k] = *(const PG8_LAS bf16x8*)(lds + PG8_SA(b, h) + aoff + m * 2048 + k * 1024); } while (0)
; #define PG8_MMA(ai, bj, At, Bt) do { __builtin_amdgcn_s_setprio(1); _Pragma("unroll") for (int m = 0; m < 4; ++m) _Pragma("unroll") for (int n = 0; n < 2; ++n) _Pragma("unroll") for (int k = 0; k < 2; ++k) \
;         acc[ai][bj][m][n] = __builtin_amdgcn_mfma_f32_16x16x32_bf16(Bt[n][k], At[m][k], acc[ai][bj][m][n], 0, 0, 0); __builtin_amdgcn_s_setprio(0); } while (0)
; #define PG8_WAIT_V(n) asm volatile("s_waitcnt vmcnt(" #n ")" ::: "memory")
; #define PG8_WAIT_L(n) asm volatile("s_waitcnt lgkmcnt(" #n ")" ::: "memory")
; #define PG8_BAR __builtin_amdgcn_s_barrier()
; #define PG8_SCHED __builtin_amdgcn_sched_barrier(0)
; template <class Epi, class Sched, bool ALIGN_EPI = false, bool SP2 = false>
; __device__ __forceinline__ void gemm_phase(PG8_LAS unsigned char* lds, const Gemm g, const Sched& S, const Epi& E) {
;     ...
;             PG8_LDA(At, 1, 1); PG8_STAGE(PG8_SB(1, 0), b3, voffB); PG8_STAGE(PG8_SB(1, 1), b3 + hstep, voffB); PG8_STAGE(PG8_SA(1, 0), a3, voffA);
;             PG8_WAIT_V(8); PG8_WAIT_L(0); PG8_BAR; PG8_MMA(1, 0, At, B0); PG8_MMA(1, 1, At, B1); PG8_BAR; PG8_SCHED;
;     ...
;         if constexpr (ALIGN_EPI) { if (wr == 0) PG8_BAR; }
;         if constexpr (!Epi::AFTER_DRAIN) { E(acc, cur, wr, wc, fr, fq, ui); S.done(cur); }
;         if (!has_next) break;
	s_add_i32 s42, s71, s33
	v_lshl_add_u64 v[226:227], v[226:227], 0, s[24:25]
	s_mov_b32 m0, s42
	ds_read_b128 v[194:197], v164 offset:49152
	ds_read_b128 v[198:201], v164 offset:50176
	ds_read_b128 v[202:205], v164 offset:51200
	ds_read_b128 v[206:209], v164 offset:52224
	ds_read_b128 v[210:213], v164 offset:53248
	ds_read_b128 v[214:217], v164 offset:54272
	ds_read_b128 v[218:221], v164 offset:55296
	ds_read_b128 v[222:225], v164 offset:56320
	global_load_lds_dwordx4 v[226:227], off
	s_add_i32 m0, s42, 0x2000
	s_add_u32 s40, s40, 0x40080
	v_lshl_add_u64 v[226:227], v[228:229], 0, s[24:25]
	s_addc_u32 s41, s41, 0
	s_add_i32 s42, s72, s33
	global_load_lds_dwordx4 v[226:227], off
	v_lshl_add_u64 v[226:227], s[40:41], 0, v[138:139]
	s_mov_b32 m0, s42
	s_nop 0
	global_load_lds_dwordx4 v[226:227], off
	v_lshl_add_u64 v[226:227], s[40:41], 0, v[142:143]
	s_add_i32 m0, s42, 0x2000
	s_nop 0
	global_load_lds_dwordx4 v[226:227], off
	v_lshl_add_u64 v[226:227], v[230:231], 0, s[24:25]
	s_mov_b32 m0, s57
	s_nop 0
	global_load_lds_dwordx4 v[226:227], off
	v_lshl_add_u64 v[226:227], v[232:233], 0, s[24:25]
	s_mov_b32 m0, s58
	s_nop 0
	global_load_lds_dwordx4 v[226:227], off
	s_waitcnt vmcnt(8)
	s_waitcnt lgkmcnt(0)
	s_barrier
	s_setprio 1
	s_waitcnt lgkmcnt(0)
	v_mfma_f32_16x16x32_bf16 v[60:63], v[148:151], v[194:197], v[60:63]
	v_mfma_f32_16x16x32_bf16 v[56:59], v[170:173], v[194:197], v[56:59]
	v_mfma_f32_16x16x32_bf16 v[44:47], v[148:151], v[202:205], v[44:47]
	v_mfma_f32_16x16x32_bf16 v[40:43], v[170:173], v[202:205], v[40:43]
	v_mfma_f32_16x16x32_bf16 v[28:31], v[148:151], v[210:213], v[28:31]
	v_mfma_f32_16x16x32_bf16 v[24:27], v[170:173], v[210:213], v[24:27]
	v_mfma_f32_16x16x32_bf16 v[12:15], v[148:151], v[218:221], v[12:15]
	v_mfma_f32_16x16x32_bf16 v[8:11], v[170:173], v[218:221], v[8:11]
	v_mfma_f32_16x16x32_bf16 v[60:63], v[166:169], v[198:201], v[60:63]
	v_mfma_f32_16x16x32_bf16 v[56:59], v[174:177], v[198:201], v[56:59]
	v_mfma_f32_16x16x32_bf16 v[44:47], v[166:169], v[206:209], v[44:47]
	v_mfma_f32_16x16x32_bf16 v[40:43], v[174:177], v[206:209], v[40:43]
	v_mfma_f32_16x16x32_bf16 v[28:31], v[166:169], v[214:217], v[28:31]
	v_mfma_f32_16x16x32_bf16 v[24:27], v[174:177], v[214:217], v[24:27]
	v_mfma_f32_16x16x32_bf16 v[12:15], v[166:169], v[222:225], v[12:15]
	v_mfma_f32_16x16x32_bf16 v[8:11], v[174:177], v[222:225], v[8:11]
	v_mfma_f32_16x16x32_bf16 v[52:55], v[178:181], v[194:197], v[52:55]
	v_mfma_f32_16x16x32_bf16 v[48:51], v[186:189], v[194:197], v[48:51]
	v_mfma_f32_16x16x32_bf16 v[36:39], v[178:181], v[202:205], v[36:39]
	v_mfma_f32_16x16x32_bf16 v[32:35], v[186:189], v[202:205], v[32:35]
	v_mfma_f32_16x16x32_bf16 v[20:23], v[178:181], v[210:213], v[20:23]
	v_mfma_f32_16x16x32_bf16 v[16:19], v[186:189], v[210:213], v[16:19]
	v_mfma_f32_16x16x32_bf16 v[4:7], v[178:181], v[218:221], v[4:7]
	v_mfma_f32_16x16x32_bf16 v[0:3], v[186:189], v[218:221], v[0:3]
	v_mfma_f32_16x16x32_bf16 v[52:55], v[182:185], v[198:201], v[52:55]
	v_mfma_f32_16x16x32_bf16 v[48:51], v[190:193], v[198:201], v[48:51]
	v_mfma_f32_16x16x32_bf16 v[36:39], v[182:185], v[206:209], v[36:39]
	v_mfma_f32_16x16x32_bf16 v[32:35], v[190:193], v[206:209], v[32:35]
	v_mfma_f32_16x16x32_bf16 v[20:23], v[182:185], v[214:217], v[20:23]
	v_mfma_f32_16x16x32_bf16 v[16:19], v[190:193], v[214:217], v[16:19]
	v_mfma_f32_16x16x32_bf16 v[4:7], v[182:185], v[222:225], v[4:7]
	v_mfma_f32_16x16x32_bf16 v[0:3], v[190:193], v[222:225], v[0:3]
	s_setprio 0
	s_barrier
	s_add_i32 s70, s70, 2
	s_add_u32 s38, s38, 0x100
	s_addc_u32 s39, s39, 0
	s_add_u32 s44, s44, 0x100
	s_addc_u32 s45, s45, 0
	s_cmp_gt_u32 s70, 13
	s_cbranch_scc0 .LBB0_509
	s_and_b64 vcc, exec, s[26:27]
	s_cbranch_vccz .LBB0_512
	s_barrier

; #define PG8_STAGE(bufoff, gbase, voff) do { _Pragma("unroll") for (int _i = 0; _i < 2; ++_i) \
;         __builtin_amdgcn_global_load_lds((const unsigned*)((const char*)(gbase) + (voff)[_i]), (PG8_LAS unsigned*)(lds + (bufoff) + ldsw + _i * 8192), 16, 0, 0); } while (0)
; #define PG8_LDA(dst, b, h) do { _Pragma("unroll") for (int m = 0; m < 4; ++m) _Pragma("unroll") for (int k = 0; k < 2; ++k) dst[m][k] = *(const PG8_LAS bf16x8*)(lds + PG8_SA(b, h) + aoff + m * 2048 + k * 1024); } while (0)
; #define PG8_LDB(dst, b, h) do { _Pragma("unroll") for (int n = 0; n < 2; ++n) _Pragma("unroll") for (int k = 0; k < 2; ++k) dst[n][k] = *(const PG8_LAS bf16x8*)(lds + PG8_SB(b, h) + boff + n * 2048 + k * 1024); } while (0)
; #define PG8_MMA(ai, bj, At, Bt) do { __builtin_amdgcn_s_setprio(1); _Pragma("unroll") for (int m = 0; m < 4; ++m) _Pragma("unroll") for (int n = 0; n < 2; ++n) _Pragma("unroll") for (int k = 0; k < 2; ++k) \
;         acc[ai][bj][m][n] = __builtin_amdgcn_mfma_f32_16x16x32_bf16(Bt[n][k], At[m][k], acc[ai][bj][m][n], 0, 0, 0); __builtin_amdgcn_s_setprio(0); } while (0)
; #define PG8_WAIT_V(n) asm volatile("s_waitcnt vmcnt(" #n ")" ::: "memory")
; #define PG8_WAIT_L(n) asm volatile("s_waitcnt lgkmcnt(" #n ")" ::: "memory")
; template <class Epi, class Sched, bool ALIGN_EPI = false, bool SP2 = false>
; __device__ __forceinline__ void gemm_phase(PG8_LAS unsigned char* lds, const Gemm g, const Sched& S, const Epi& E) {
;     ...
;             const bool last = (t == nt - 2);
;             const char* a1 = cA + (size_t)(t + 1) * kstep;
;             const char* a2 = last ? nA : cA + (size_t)(t + 2) * kstep; const char* b2 = last ? nB : cB + (size_t)(t + 2) * kstep;
;             const char* a3 = a2 + kstep; const char* b3 = b2 + kstep;
;             if (last && has_next) S.a_ready(nxt, ui + 1);
;             if constexpr (SP2) {
;             PG8_LDB(B0, 0, 0); PG8_LDB(B1, 0, 1); PG8_SCHED; PG8_LDA(At, 0, 0); PG8_STAGE(PG8_SA(1, 1), a1 + hstep, voffA);
;             PG8_WAIT_V(8); PG8_WAIT_L(0); PG8_BAR; PG8_MMA(0, 0, At, B0); PG8_MMA(0, 1, At, B1); PG8_BAR; PG8_SCHED;
;             PG8_LDA(At, 0, 1); PG8_STAGE(PG8_SB(0, 0), b2, voffB); PG8_STAGE(PG8_SB(0, 1), b2 + hstep, voffB); PG8_STAGE(PG8_SA(0, 0), a2, voffA);
;             PG8_WAIT_V(8); PG8_WAIT_L(0); PG8_BAR; PG8_MMA(1, 0, At, B0); PG8_MMA(1, 1, At, B1); PG8_BAR; PG8_SCHED;
.LBB0_607:
	ds_read_b128 v[128:131], v170
	ds_read_b128 v[132:135], v170 offset:1024
	ds_read_b128 v[174:177], v170 offset:2048
	ds_read_b128 v[178:181], v170 offset:3072
	ds_read_b128 v[182:185], v171
	ds_read_b128 v[186:189], v171 offset:1024
	ds_read_b128 v[190:193], v171 offset:2048
	ds_read_b128 v[194:197], v171 offset:3072
	s_add_u32 s30, s28, 0xfffc0080
	s_addc_u32 s31, s29, -1
	s_cmp_eq_u32 s59, 12
	s_cselect_b32 s35, s21, s31
	s_cselect_b32 s34, s55, s30
	s_cselect_b32 s31, s19, s58
	s_cselect_b32 s30, s56, s57
	v_lshl_add_u64 v[160:161], s[28:29], 0, v[152:153]
	s_add_i32 m0, s38, 0xc000
	ds_read_b128 v[198:201], v172
	ds_read_b128 v[202:205], v172 offset:1024
	ds_read_b128 v[206:209], v172 offset:2048
	ds_read_b128 v[210:213], v172 offset:3072
	ds_read_b128 v[214:217], v172 offset:4096
	ds_read_b128 v[218:221], v172 offset:5120
	ds_read_b128 v[222:225], v172 offset:6144
	ds_read_b128 v[226:229], v172 offset:7168
	global_load_lds_dwordx4 v[160:161], off
	v_lshl_add_u64 v[160:161], s[28:29], 0, v[154:155]
	s_add_i32 m0, s38, 0xe000
	s_nop 0
	global_load_lds_dwordx4 v[160:161], off
	s_waitcnt vmcnt(8)
	s_waitcnt lgkmcnt(0)
	s_barrier
	s_setprio 1
	s_waitcnt lgkmcnt(0)
	v_mfma_f32_16x16x32_bf16 v[124:127], v[128:131], v[198:201], v[124:127]
	v_mfma_f32_16x16x32_bf16 v[120:123], v[174:177], v[198:201], v[120:123]
	v_mfma_f32_16x16x32_bf16 v[116:119], v[128:131], v[206:209], v[116:119]
	v_mfma_f32_16x16x32_bf16 v[112:115], v[174:177], v[206:209], v[112:115]
	v_mfma_f32_16x16x32_bf16 v[108:111], v[128:131], v[214:217], v[108:111]
	v_mfma_f32_16x16x32_bf16 v[104:107], v[174:177], v[214:217], v[104:107]
	v_mfma_f32_16x16x32_bf16 v[100:103], v[128:131], v[222:225], v[100:103]
	v_mfma_f32_16x16x32_bf16 v[96:99], v[174:177], v[222:225], v[96:99]
	v_mfma_f32_16x16x32_bf16 v[124:127], v[132:135], v[202:205], v[124:127]
	v_mfma_f32_16x16x32_bf16 v[120:123], v[178:181], v[202:205], v[120:123]
	v_mfma_f32_16x16x32_bf16 v[116:119], v[132:135], v[210:213], v[116:119]
	v_mfma_f32_16x16x32_bf16 v[112:115], v[178:181], v[210:213], v[112:115]
	v_mfma_f32_16x16x32_bf16 v[108:111], v[132:135], v[218:221], v[108:111]
	v_mfma_f32_16x16x32_bf16 v[104:107], v[178:181], v[218:221], v[104:107]
	v_mfma_f32_16x16x32_bf16 v[100:103], v[132:135], v[226:229], v[100:103]
	v_mfma_f32_16x16x32_bf16 v[96:99], v[178:181], v[226:229], v[96:99]
	v_mfma_f32_16x16x32_bf16 v[60:63], v[182:185], v[198:201], v[60:63]
	v_mfma_f32_16x16x32_bf16 v[56:59], v[190:193], v[198:201], v[56:59]
	v_mfma_f32_16x16x32_bf16 v[52:55], v[182:185], v[206:209], v[52:55]
	v_mfma_f32_16x16x32_bf16 v[48:51], v[190:193], v[206:209], v[48:51]
	v_mfma_f32_16x16x32_bf16 v[44:47], v[182:185], v[214:217], v[44:47]
	v_mfma_f32_16x16x32_bf16 v[40:43], v[190:193], v[214:217], v[40:43]
	v_mfma_f32_16x16x32_bf16 v[36:39], v[182:185], v[222:225], v[36:39]
	v_mfma_f32_16x16x32_bf16 v[32:35], v[190:193], v[222:225], v[32:35]
	v_mfma_f32_16x16x32_bf16 v[60:63], v[186:189], v[202:205], v[60:63]
	v_mfma_f32_16x16x32_bf16 v[56:59], v[194:197], v[202:205], v[56:59]
	v_mfma_f32_16x16x32_bf16 v[52:55], v[186:189], v[210:213], v[52:55]
	v_mfma_f32_16x16x32_bf16 v[48:51], v[194:197], v[210:213], v[48:51]
	v_mfma_f32_16x16x32_bf16 v[44:47], v[186:189], v[218:221], v[44:47]
	v_mfma_f32_16x16x32_bf16 v[40:43], v[194:197], v[218:221], v[40:43]
	v_mfma_f32_16x16x32_bf16 v[36:39], v[186:189], v[226:229], v[36:39]
	v_mfma_f32_16x16x32_bf16 v[32:35], v[194:197], v[226:229], v[32:35]
	s_setprio 0
	s_barrier
	s_add_i32 s60, s45, s33
	v_lshl_add_u64 v[160:161], s[30:31], 0, v[138:139]
	s_mov_b32 m0, s60
	ds_read_b128 v[198:201], v172 offset:16384
	ds_read_b128 v[202:205], v172 offset:17408
	ds_read_b128 v[206:209], v172 offset:18432
	ds_read_b128 v[210:213], v172 offset:19456
	ds_read_b128 v[214:217], v172 offset:20480
	ds_read_b128 v[218:221], v172 offset:21504
	ds_read_b128 v[222:225], v172 offset:22528
	ds_read_b128 v[226:229], v172 offset:23552
	global_load_lds_dwordx4 v[160:161], off
	s_add_i32 m0, s60, 0x2000
	s_add_u32 s60, s30, 0x40000
	v_lshl_add_u64 v[230:231], s[30:31], 0, v[142:143]
	s_addc_u32 s61, s31, 0
	s_add_i32 s62, s50, s33
	global_load_lds_dwordx4 v[230:231], off
	v_lshl_add_u64 v[232:233], s[60:61], 0, v[138:139]
	s_mov_b32 m0, s62
	v_lshl_add_u64 v[234:235], s[34:35], 0, v[140:141]
	global_load_lds_dwordx4 v[232:233], off
	v_lshl_add_u64 v[232:233], s[60:61], 0, v[142:143]
	s_add_i32 m0, s62, 0x2000
	s_nop 0
	global_load_lds_dwordx4 v[232:233], off
	v_lshl_add_u64 v[232:233], s[34:35], 0, v[136:137]
	s_mov_b32 m0, s38
	s_nop 0
	global_load_lds_dwordx4 v[232:233], off
	s_mov_b32 m0, s39
	s_nop 0
	global_load_lds_dwordx4 v[234:235], off
	s_waitcnt vmcnt(8)
	s_waitcnt lgkmcnt(0)
	s_barrier
; #define PG8_STAGE(bufoff, gbase, voff) do { _Pragma("unroll") for (int _i = 0; _i < 2; ++_i) \
;         __builtin_amdgcn_global_load_lds((const unsigned*)((const char*)(gbase) + (voff)[_i]), (PG8_LAS unsigned*)(lds + (bufoff) + ldsw + _i * 8192), 16, 0, 0); } while (0)
; #define PG8_LDA(dst, b, h) do { _Pragma("unroll") for (int m = 0; m < 4; ++m) _Pragma("unroll") for (int k = 0; k < 2; ++k) dst[m][k] = *(const PG8_LAS bf16x8*)(lds + PG8_SA(b, h) + aoff + m * 2048 + k * 1024); } while (0)
; #define PG8_LDB(dst, b, h) do { _Pragma("unroll") for (int n = 0; n < 2; ++n) _Pragma("unroll") for (int k = 0; k < 2; ++k) dst[n][k] = *(const PG8_LAS bf16x8*)(lds + PG8_SB(b, h) + boff + n * 2048 + k * 1024); } while (0)
; #define PG8_MMA(ai, bj, At, Bt) do { __builtin_amdgcn_s_setprio(1); _Pragma("unroll") for (int m = 0; m < 4; ++m) _Pragma("unroll") for (int n = 0; n < 2; ++n) _Pragma("unroll") for (int k = 0; k < 2; ++k) \
;         acc[ai][bj][m][n] = __builtin_amdgcn_mfma_f32_16x16x32_bf16(Bt[n][k], At[m][k], acc[ai][bj][m][n], 0, 0, 0); __builtin_amdgcn_s_setprio(0); } while (0)
; #define PG8_WAIT_V(n) asm volatile("s_waitcnt vmcnt(" #n ")" ::: "memory")
; #define PG8_WAIT_L(n) asm volatile("s_waitcnt lgkmcnt(" #n ")" ::: "memory")
; #define PG8_BAR __builtin_amdgcn_s_barrier()
; #define PG8_SCHED __builtin_amdgcn_sched_barrier(0)
; template <class Epi, class Sched, bool ALIGN_EPI = false, bool SP2 = false>
; __device__ __forceinline__ void gemm_phase(PG8_LAS unsigned char* lds, const Gemm g, const Sched& S, const Epi& E) {
;     ...
;             PG8_WAIT_V(8); PG8_WAIT_L(0); PG8_BAR; PG8_MMA(1, 0, At, B0); PG8_MMA(1, 1, At, B1); PG8_BAR; PG8_SCHED;
;             PG8_LDB(B0, 1, 0); PG8_LDB(B1, 1, 1); PG8_SCHED; PG8_LDA(At, 1, 0); PG8_STAGE(PG8_SA(0, 1), a2 + hstep, voffA);
;             PG8_WAIT_V(8); PG8_WAIT_L(0); PG8_BAR; PG8_MMA(0, 0, At, B0); PG8_MMA(0, 1, At, B1); PG8_BAR; PG8_SCHED;
	s_setprio 1
	s_waitcnt lgkmcnt(0)
	v_mfma_f32_16x16x32_bf16 v[92:95], v[128:131], v[198:201], v[92:95]
	v_mfma_f32_16x16x32_bf16 v[88:91], v[174:177], v[198:201], v[88:91]
	v_mfma_f32_16x16x32_bf16 v[84:87], v[128:131], v[206:209], v[84:87]
	v_mfma_f32_16x16x32_bf16 v[80:83], v[174:177], v[206:209], v[80:83]
	v_mfma_f32_16x16x32_bf16 v[76:79], v[128:131], v[214:217], v[76:79]
	v_mfma_f32_16x16x32_bf16 v[72:75], v[174:177], v[214:217], v[72:75]
	v_mfma_f32_16x16x32_bf16 v[68:71], v[128:131], v[222:225], v[68:71]
	v_mfma_f32_16x16x32_bf16 v[64:67], v[174:177], v[222:225], v[64:67]
	v_mfma_f32_16x16x32_bf16 v[92:95], v[132:135], v[202:205], v[92:95]
	v_mfma_f32_16x16x32_bf16 v[88:91], v[178:181], v[202:205], v[88:91]
	v_mfma_f32_16x16x32_bf16 v[84:87], v[132:135], v[210:213], v[84:87]
	v_mfma_f32_16x16x32_bf16 v[80:83], v[178:181], v[210:213], v[80:83]
	v_mfma_f32_16x16x32_bf16 v[76:79], v[132:135], v[218:221], v[76:79]
	v_mfma_f32_16x16x32_bf16 v[72:75], v[178:181], v[218:221], v[72:75]
	v_mfma_f32_16x16x32_bf16 v[68:71], v[132:135], v[226:229], v[68:71]
	v_mfma_f32_16x16x32_bf16 v[64:67], v[178:181], v[226:229], v[64:67]
	v_mfma_f32_16x16x32_bf16 v[28:31], v[182:185], v[198:201], v[28:31]
	v_mfma_f32_16x16x32_bf16 v[24:27], v[190:193], v[198:201], v[24:27]
	v_mfma_f32_16x16x32_bf16 v[20:23], v[182:185], v[206:209], v[20:23]
	v_mfma_f32_16x16x32_bf16 v[16:19], v[190:193], v[206:209], v[16:19]
	v_mfma_f32_16x16x32_bf16 v[12:15], v[182:185], v[214:217], v[12:15]
	v_mfma_f32_16x16x32_bf16 v[8:11], v[190:193], v[214:217], v[8:11]
	v_mfma_f32_16x16x32_bf16 v[4:7], v[182:185], v[222:225], v[4:7]
	v_mfma_f32_16x16x32_bf16 v[0:3], v[190:193], v[222:225], v[0:3]
	v_mfma_f32_16x16x32_bf16 v[28:31], v[186:189], v[202:205], v[28:31]
	v_mfma_f32_16x16x32_bf16 v[24:27], v[194:197], v[202:205], v[24:27]
	v_mfma_f32_16x16x32_bf16 v[20:23], v[186:189], v[210:213], v[20:23]
	v_mfma_f32_16x16x32_bf16 v[16:19], v[194:197], v[210:213], v[16:19]
	v_mfma_f32_16x16x32_bf16 v[12:15], v[186:189], v[218:221], v[12:15]
	v_mfma_f32_16x16x32_bf16 v[8:11], v[194:197], v[218:221], v[8:11]
	v_mfma_f32_16x16x32_bf16 v[4:7], v[186:189], v[226:229], v[4:7]
	v_mfma_f32_16x16x32_bf16 v[0:3], v[194:197], v[226:229], v[0:3]
	s_setprio 0
	s_barrier
	s_add_i32 s60, 0, 0x18000
	s_add_i32 s61, 0, 0x1c000
	v_add_u32_e32 v178, s60, v163
	v_add_u32_e32 v194, s61, v163
	ds_read_b128 v[128:131], v178
	ds_read_b128 v[132:135], v178 offset:1024
	ds_read_b128 v[174:177], v178 offset:2048
	ds_read_b128 v[178:181], v178 offset:3072
	ds_read_b128 v[182:185], v194
	ds_read_b128 v[186:189], v194 offset:1024
	ds_read_b128 v[190:193], v194 offset:2048
	ds_read_b128 v[194:197], v194 offset:3072
	s_add_u32 s34, s34, 0x40000
	s_addc_u32 s35, s35, 0
	s_mov_b32 m0, s40
	v_lshl_add_u64 v[236:237], s[34:35], 0, v[136:137]
	ds_read_b128 v[198:201], v172 offset:32768
	ds_read_b128 v[202:205], v172 offset:33792
	ds_read_b128 v[206:209], v172 offset:34816
	ds_read_b128 v[210:213], v172 offset:35840
	ds_read_b128 v[214:217], v172 offset:36864
	ds_read_b128 v[218:221], v172 offset:37888
	ds_read_b128 v[222:225], v172 offset:38912
	ds_read_b128 v[226:229], v172 offset:39936
	global_load_lds_dwordx4 v[236:237], off
	v_lshl_add_u64 v[236:237], s[34:35], 0, v[140:141]
	s_mov_b32 m0, s41
	s_nop 0
	global_load_lds_dwordx4 v[236:237], off
	s_waitcnt vmcnt(8)
	s_waitcnt lgkmcnt(0)
	s_barrier
	s_setprio 1
	s_waitcnt lgkmcnt(0)
	v_mfma_f32_16x16x32_bf16 v[124:127], v[128:131], v[198:201], v[124:127]
	v_mfma_f32_16x16x32_bf16 v[120:123], v[174:177], v[198:201], v[120:123]
	v_mfma_f32_16x16x32_bf16 v[116:119], v[128:131], v[206:209], v[116:119]
	v_mfma_f32_16x16x32_bf16 v[112:115], v[174:177], v[206:209], v[112:115]
	v_mfma_f32_16x16x32_bf16 v[108:111], v[128:131], v[214:217], v[108:111]
	v_mfma_f32_16x16x32_bf16 v[104:107], v[174:177], v[214:217], v[104:107]
	v_mfma_f32_16x16x32_bf16 v[100:103], v[128:131], v[222:225], v[100:103]
	v_mfma_f32_16x16x32_bf16 v[96:99], v[174:177], v[222:225], v[96:99]
	v_mfma_f32_16x16x32_bf16 v[124:127], v[132:135], v[202:205], v[124:127]
	v_mfma_f32_16x16x32_bf16 v[120:123], v[178:181], v[202:205], v[120:123]
	v_mfma_f32_16x16x32_bf16 v[116:119], v[132:135], v[210:213], v[116:119]
	v_mfma_f32_16x16x32_bf16 v[112:115], v[178:181], v[210:213], v[112:115]
	v_mfma_f32_16x16x32_bf16 v[108:111], v[132:135], v[218:221], v[108:111]
	v_mfma_f32_16x16x32_bf16 v[104:107], v[178:181], v[218:221], v[104:107]
	v_mfma_f32_16x16x32_bf16 v[100:103], v[132:135], v[226:229], v[100:103]
	v_mfma_f32_16x16x32_bf16 v[96:99], v[178:181], v[226:229], v[96:99]
	v_mfma_f32_16x16x32_bf16 v[60:63], v[182:185], v[198:201], v[60:63]
	v_mfma_f32_16x16x32_bf16 v[56:59], v[190:193], v[198:201], v[56:59]
	v_mfma_f32_16x16x32_bf16 v[52:55], v[182:185], v[206:209], v[52:55]
	v_mfma_f32_16x16x32_bf16 v[48:51], v[190:193], v[206:209], v[48:51]
	v_mfma_f32_16x16x32_bf16 v[44:47], v[182:185], v[214:217], v[44:47]
	v_mfma_f32_16x16x32_bf16 v[40:43], v[190:193], v[214:217], v[40:43]
	v_mfma_f32_16x16x32_bf16 v[36:39], v[182:185], v[222:225], v[36:39]
	v_mfma_f32_16x16x32_bf16 v[32:35], v[190:193], v[222:225], v[32:35]
	v_mfma_f32_16x16x32_bf16 v[60:63], v[186:189], v[202:205], v[60:63]
	v_mfma_f32_16x16x32_bf16 v[56:59], v[194:197], v[202:205], v[56:59]
	v_mfma_f32_16x16x32_bf16 v[52:55], v[186:189], v[210:213], v[52:55]
	v_mfma_f32_16x16x32_bf16 v[48:51], v[194:197], v[210:213], v[48:51]
	v_mfma_f32_16x16x32_bf16 v[44:47], v[186:189], v[218:221], v[44:47]
	v_mfma_f32_16x16x32_bf16 v[40:43], v[194:197], v[218:221], v[40:43]
	v_mfma_f32_16x16x32_bf16 v[36:39], v[186:189], v[226:229], v[36:39]
	v_mfma_f32_16x16x32_bf16 v[32:35], v[194:197], v[226:229], v[32:35]
	s_setprio 0
	s_barrier
; #define PG8_STAGE(bufoff, gbase, voff) do { _Pragma("unroll") for (int _i = 0; _i < 2; ++_i) \
;         __builtin_amdgcn_global_load_lds((const unsigned*)((const char*)(gbase) + (voff)[_i]), (PG8_LAS unsigned*)(lds + (bufoff) + ldsw + _i * 8192), 16, 0, 0); } while (0)
; #define PG8_LDA(dst, b, h) do { _Pragma("unroll") for (int m = 0; m < 4; ++m) _Pragma("unroll") for (int k = 0; k < 2; ++k) dst[m][k] = *(const PG8_LAS bf16x8*)(lds + PG8_SA(b, h) + aoff + m * 2048 + k * 1024); } while (0)
; #define PG8_MMA(ai, bj, At, Bt) do { __builtin_amdgcn_s_setprio(1); _Pragma("unroll") for (int m = 0; m < 4; ++m) _Pragma("unroll") for (int n = 0; n < 2; ++n) _Pragma("unroll") for (int k = 0; k < 2; ++k) \
;         acc[ai][bj][m][n] = __builtin_amdgcn_mfma_f32_16x16x32_bf16(Bt[n][k], At[m][k], acc[ai][bj][m][n], 0, 0, 0); __builtin_amdgcn_s_setprio(0); } while (0)
; #define PG8_WAIT_V(n) asm volatile("s_waitcnt vmcnt(" #n ")" ::: "memory")
; #define PG8_WAIT_L(n) asm volatile("s_waitcnt lgkmcnt(" #n ")" ::: "memory")
; #define PG8_BAR __builtin_amdgcn_s_barrier()
; #define PG8_SCHED __builtin_amdgcn_sched_barrier(0)
; template <class Epi, class Sched, bool ALIGN_EPI = false, bool SP2 = false>
; __device__ __forceinline__ void gemm_phase(PG8_LAS unsigned char* lds, const Gemm g, const Sched& S, const Epi& E) {
;     ...
;             PG8_LDA(At, 1, 1); PG8_STAGE(PG8_SB(1, 0), b3, voffB); PG8_STAGE(PG8_SB(1, 1), b3 + hstep, voffB); PG8_STAGE(PG8_SA(1, 0), a3, voffA);
;             PG8_WAIT_V(8); PG8_WAIT_L(0); PG8_BAR; PG8_MMA(1, 0, At, B0); PG8_MMA(1, 1, At, B1); PG8_BAR; PG8_SCHED;
;     ...
;         if constexpr (ALIGN_EPI) { if (wr == 0) PG8_BAR; }
;         if constexpr (!Epi::AFTER_DRAIN) { E(acc, cur, wr, wc, fr, fq, ui); S.done(cur); }
;         if (!has_next) break;
	s_add_i32 s34, s60, s33
	v_lshl_add_u64 v[160:161], v[160:161], 0, s[16:17]
	s_mov_b32 m0, s34
	ds_read_b128 v[198:201], v172 offset:49152
	ds_read_b128 v[202:205], v172 offset:50176
	ds_read_b128 v[206:209], v172 offset:51200
	ds_read_b128 v[210:213], v172 offset:52224
	ds_read_b128 v[214:217], v172 offset:53248
	ds_read_b128 v[218:221], v172 offset:54272
	ds_read_b128 v[222:225], v172 offset:55296
	ds_read_b128 v[226:229], v172 offset:56320
	global_load_lds_dwordx4 v[160:161], off
	s_add_i32 m0, s34, 0x2000
	s_add_u32 s30, s30, 0x40080
	v_lshl_add_u64 v[160:161], v[230:231], 0, s[16:17]
	s_addc_u32 s31, s31, 0
	s_add_i32 s34, s61, s33
	global_load_lds_dwordx4 v[160:161], off
	v_lshl_add_u64 v[160:161], s[30:31], 0, v[138:139]
	s_mov_b32 m0, s34
	s_nop 0
	global_load_lds_dwordx4 v[160:161], off
	v_lshl_add_u64 v[160:161], s[30:31], 0, v[142:143]
	s_add_i32 m0, s34, 0x2000
	s_nop 0
	global_load_lds_dwordx4 v[160:161], off
	v_lshl_add_u64 v[160:161], v[232:233], 0, s[16:17]
	s_mov_b32 m0, s42
	s_nop 0
	global_load_lds_dwordx4 v[160:161], off
	v_lshl_add_u64 v[160:161], v[234:235], 0, s[16:17]
	s_mov_b32 m0, s43
	s_nop 0
	global_load_lds_dwordx4 v[160:161], off
	s_waitcnt vmcnt(8)
	s_waitcnt lgkmcnt(0)
	s_barrier
	s_setprio 1
	s_waitcnt lgkmcnt(0)
	v_mfma_f32_16x16x32_bf16 v[92:95], v[128:131], v[198:201], v[92:95]
	v_mfma_f32_16x16x32_bf16 v[88:91], v[174:177], v[198:201], v[88:91]
	v_mfma_f32_16x16x32_bf16 v[84:87], v[128:131], v[206:209], v[84:87]
	v_mfma_f32_16x16x32_bf16 v[80:83], v[174:177], v[206:209], v[80:83]
	v_mfma_f32_16x16x32_bf16 v[76:79], v[128:131], v[214:217], v[76:79]
	v_mfma_f32_16x16x32_bf16 v[72:75], v[174:177], v[214:217], v[72:75]
	v_mfma_f32_16x16x32_bf16 v[68:71], v[128:131], v[222:225], v[68:71]
	v_mfma_f32_16x16x32_bf16 v[64:67], v[174:177], v[222:225], v[64:67]
	v_mfma_f32_16x16x32_bf16 v[92:95], v[132:135], v[202:205], v[92:95]
	v_mfma_f32_16x16x32_bf16 v[88:91], v[178:181], v[202:205], v[88:91]
	v_mfma_f32_16x16x32_bf16 v[84:87], v[132:135], v[210:213], v[84:87]
	v_mfma_f32_16x16x32_bf16 v[80:83], v[178:181], v[210:213], v[80:83]
	v_mfma_f32_16x16x32_bf16 v[76:79], v[132:135], v[218:221], v[76:79]
	v_mfma_f32_16x16x32_bf16 v[72:75], v[178:181], v[218:221], v[72:75]
	v_mfma_f32_16x16x32_bf16 v[68:71], v[132:135], v[226:229], v[68:71]
	v_mfma_f32_16x16x32_bf16 v[64:67], v[178:181], v[226:229], v[64:67]
	v_mfma_f32_16x16x32_bf16 v[28:31], v[182:185], v[198:201], v[28:31]
	v_mfma_f32_16x16x32_bf16 v[24:27], v[190:193], v[198:201], v[24:27]
	v_mfma_f32_16x16x32_bf16 v[20:23], v[182:185], v[206:209], v[20:23]
	v_mfma_f32_16x16x32_bf16 v[16:19], v[190:193], v[206:209], v[16:19]
	v_mfma_f32_16x16x32_bf16 v[12:15], v[182:185], v[214:217], v[12:15]
	v_mfma_f32_16x16x32_bf16 v[8:11], v[190:193], v[214:217], v[8:11]
	v_mfma_f32_16x16x32_bf16 v[4:7], v[182:185], v[222:225], v[4:7]
	v_mfma_f32_16x16x32_bf16 v[0:3], v[190:193], v[222:225], v[0:3]
	v_mfma_f32_16x16x32_bf16 v[28:31], v[186:189], v[202:205], v[28:31]
	v_mfma_f32_16x16x32_bf16 v[24:27], v[194:197], v[202:205], v[24:27]
	v_mfma_f32_16x16x32_bf16 v[20:23], v[186:189], v[210:213], v[20:23]
	v_mfma_f32_16x16x32_bf16 v[16:19], v[194:197], v[210:213], v[16:19]
	v_mfma_f32_16x16x32_bf16 v[12:15], v[186:189], v[218:221], v[12:15]
	v_mfma_f32_16x16x32_bf16 v[8:11], v[194:197], v[218:221], v[8:11]
	v_mfma_f32_16x16x32_bf16 v[4:7], v[186:189], v[226:229], v[4:7]
	v_mfma_f32_16x16x32_bf16 v[0:3], v[194:197], v[226:229], v[0:3]
	s_setprio 0
	s_barrier
	s_add_i32 s59, s59, 2
	s_add_u32 s28, s28, 0x100
	s_addc_u32 s29, s29, 0
	s_add_u32 s57, s57, 0x100
	s_addc_u32 s58, s58, 0
	s_cmp_gt_u32 s59, 13
	s_cbranch_scc0 .LBB0_607
	s_and_b64 vcc, exec, s[0:1]
	s_cbranch_vccz .LBB0_610
	s_barrier

; #define PG8_STAGE(bufoff, gbase, voff) do { _Pragma("unroll") for (int _i = 0; _i < 2; ++_i) \
;         __builtin_amdgcn_global_load_lds((const unsigned*)((const char*)(gbase) + (voff)[_i]), (PG8_LAS unsigned*)(lds + (bufoff) + ldsw + _i * 8192), 16, 0, 0); } while (0)
; #define PG8_LDA(dst, b, h) do { _Pragma("unroll") for (int m = 0; m < 4; ++m) _Pragma("unroll") for (int k = 0; k < 2; ++k) dst[m][k] = *(const PG8_LAS bf16x8*)(lds + PG8_SA(b, h) + aoff + m * 2048 + k * 1024); } while (0)
; #define PG8_LDB(dst, b, h) do { _Pragma("unroll") for (int n = 0; n < 2; ++n) _Pragma("unroll") for (int k = 0; k < 2; ++k) dst[n][k] = *(const PG8_LAS bf16x8*)(lds + PG8_SB(b, h) + boff + n * 2048 + k * 1024); } while (0)
; #define PG8_MMA(ai, bj, At, Bt) do { __builtin_amdgcn_s_setprio(1); _Pragma("unroll") for (int m = 0; m < 4; ++m) _Pragma("unroll") for (int n = 0; n < 2; ++n) _Pragma("unroll") for (int k = 0; k < 2; ++k) \
;         acc[ai][bj][m][n] = __builtin_amdgcn_mfma_f32_16x16x32_bf16(Bt[n][k], At[m][k], acc[ai][bj][m][n], 0, 0, 0); __builtin_amdgcn_s_setprio(0); } while (0)
; #define PG8_WAIT_V(n) asm volatile("s_waitcnt vmcnt(" #n ")" ::: "memory")
; #define PG8_WAIT_L(n) asm volatile("s_waitcnt lgkmcnt(" #n ")" ::: "memory")
; template <class Epi, class Sched, bool ALIGN_EPI = false, bool SP2 = false>
; __device__ __forceinline__ void gemm_phase(PG8_LAS unsigned char* lds, const Gemm g, const Sched& S, const Epi& E) {
;     ...
;             const bool last = (t == nt - 2);
;             const char* a1 = cA + (size_t)(t + 1) * kstep;
;             const char* a2 = last ? nA : cA + (size_t)(t + 2) * kstep; const char* b2 = last ? nB : cB + (size_t)(t + 2) * kstep;
;             const char* a3 = a2 + kstep; const char* b3 = b2 + kstep;
;             if (last && has_next) S.a_ready(nxt, ui + 1);
;             if constexpr (SP2) {
;             PG8_LDB(B0, 0, 0); PG8_LDB(B1, 0, 1); PG8_SCHED; PG8_LDA(At, 0, 0); PG8_STAGE(PG8_SA(1, 1), a1 + hstep, voffA);
;             PG8_WAIT_V(8); PG8_WAIT_L(0); PG8_BAR; PG8_MMA(0, 0, At, B0); PG8_MMA(0, 1, At, B1); PG8_BAR; PG8_SCHED;
;             PG8_LDA(At, 0, 1); PG8_STAGE(PG8_SB(0, 0), b2, voffB); PG8_STAGE(PG8_SB(0, 1), b2 + hstep, voffB); PG8_STAGE(PG8_SA(0, 0), a2, voffA);
;             PG8_WAIT_V(8); PG8_WAIT_L(0); PG8_BAR; PG8_MMA(1, 0, At, B0); PG8_MMA(1, 1, At, B1); PG8_BAR; PG8_SCHED;
.LBB0_960:
	ds_read_b128 v[120:123], v245
	ds_read_b128 v[128:131], v245 offset:1024
	ds_read_b128 v[136:139], v245 offset:2048
	ds_read_b128 v[140:143], v245 offset:3072
	ds_read_b128 v[144:147], v246
	ds_read_b128 v[148:151], v246 offset:1024
	ds_read_b128 v[152:155], v246 offset:2048
	ds_read_b128 v[156:159], v246 offset:3072
	s_add_u32 s34, s30, 0xfffc0080
	s_addc_u32 s35, s31, -1
	s_cmp_eq_u32 s57, 12
	s_cselect_b32 s37, s23, s35
	s_cselect_b32 s36, s29, s34
	s_cselect_b32 s35, s21, s56
	s_cselect_b32 s34, s54, s55
	v_lshl_add_u64 v[204:205], s[30:31], 0, v[200:201]
	s_add_i32 m0, s41, 0xc000
	ds_read_b128 v[160:163], v247
	ds_read_b128 v[164:167], v247 offset:1024
	ds_read_b128 v[168:171], v247 offset:2048
	ds_read_b128 v[172:175], v247 offset:3072
	ds_read_b128 v[176:179], v247 offset:4096
	ds_read_b128 v[180:183], v247 offset:5120
	ds_read_b128 v[184:187], v247 offset:6144
	ds_read_b128 v[188:191], v247 offset:7168
	global_load_lds_dwordx4 v[204:205], off
	v_lshl_add_u64 v[204:205], s[30:31], 0, v[202:203]
	s_add_i32 m0, s41, 0xe000
	s_nop 0
	global_load_lds_dwordx4 v[204:205], off
	s_waitcnt vmcnt(8)
	s_waitcnt lgkmcnt(0)
	s_barrier
	s_setprio 1
	s_waitcnt lgkmcnt(0)
	v_mfma_f32_16x16x32_bf16 v[132:135], v[120:123], v[160:163], v[132:135]
	v_mfma_f32_16x16x32_bf16 v[124:127], v[136:139], v[160:163], v[124:127]
	v_mfma_f32_16x16x32_bf16 v[108:111], v[120:123], v[168:171], v[108:111]
	v_mfma_f32_16x16x32_bf16 v[104:107], v[136:139], v[168:171], v[104:107]
	v_mfma_f32_16x16x32_bf16 v[92:95], v[120:123], v[176:179], v[92:95]
	v_mfma_f32_16x16x32_bf16 v[88:91], v[136:139], v[176:179], v[88:91]
	v_mfma_f32_16x16x32_bf16 v[76:79], v[120:123], v[184:187], v[76:79]
	v_mfma_f32_16x16x32_bf16 v[72:75], v[136:139], v[184:187], v[72:75]
	v_mfma_f32_16x16x32_bf16 v[132:135], v[128:131], v[164:167], v[132:135]
	v_mfma_f32_16x16x32_bf16 v[124:127], v[140:143], v[164:167], v[124:127]
	v_mfma_f32_16x16x32_bf16 v[108:111], v[128:131], v[172:175], v[108:111]
	v_mfma_f32_16x16x32_bf16 v[104:107], v[140:143], v[172:175], v[104:107]
	v_mfma_f32_16x16x32_bf16 v[92:95], v[128:131], v[180:183], v[92:95]
	v_mfma_f32_16x16x32_bf16 v[88:91], v[140:143], v[180:183], v[88:91]
	v_mfma_f32_16x16x32_bf16 v[76:79], v[128:131], v[188:191], v[76:79]
	v_mfma_f32_16x16x32_bf16 v[72:75], v[140:143], v[188:191], v[72:75]
	v_mfma_f32_16x16x32_bf16 v[116:119], v[144:147], v[160:163], v[116:119]
	v_mfma_f32_16x16x32_bf16 v[112:115], v[152:155], v[160:163], v[112:115]
	v_mfma_f32_16x16x32_bf16 v[100:103], v[144:147], v[168:171], v[100:103]
	v_mfma_f32_16x16x32_bf16 v[96:99], v[152:155], v[168:171], v[96:99]
	v_mfma_f32_16x16x32_bf16 v[84:87], v[144:147], v[176:179], v[84:87]
	v_mfma_f32_16x16x32_bf16 v[80:83], v[152:155], v[176:179], v[80:83]
	v_mfma_f32_16x16x32_bf16 v[68:71], v[144:147], v[184:187], v[68:71]
	v_mfma_f32_16x16x32_bf16 v[64:67], v[152:155], v[184:187], v[64:67]
	v_mfma_f32_16x16x32_bf16 v[116:119], v[148:151], v[164:167], v[116:119]
	v_mfma_f32_16x16x32_bf16 v[112:115], v[156:159], v[164:167], v[112:115]
	v_mfma_f32_16x16x32_bf16 v[100:103], v[148:151], v[172:175], v[100:103]
	v_mfma_f32_16x16x32_bf16 v[96:99], v[156:159], v[172:175], v[96:99]
	v_mfma_f32_16x16x32_bf16 v[84:87], v[148:151], v[180:183], v[84:87]
	v_mfma_f32_16x16x32_bf16 v[80:83], v[156:159], v[180:183], v[80:83]
	v_mfma_f32_16x16x32_bf16 v[68:71], v[148:151], v[188:191], v[68:71]
	v_mfma_f32_16x16x32_bf16 v[64:67], v[156:159], v[188:191], v[64:67]
	s_setprio 0
	s_barrier
	s_add_i32 s58, s51, s40
	v_lshl_add_u64 v[204:205], s[34:35], 0, v[194:195]
	s_mov_b32 m0, s58
	ds_read_b128 v[160:163], v247 offset:16384
	ds_read_b128 v[164:167], v247 offset:17408
	ds_read_b128 v[168:171], v247 offset:18432
	ds_read_b128 v[172:175], v247 offset:19456
	ds_read_b128 v[176:179], v247 offset:20480
	ds_read_b128 v[180:183], v247 offset:21504
	ds_read_b128 v[184:187], v247 offset:22528
	ds_read_b128 v[188:191], v247 offset:23552
	global_load_lds_dwordx4 v[204:205], off
	s_add_i32 m0, s58, 0x2000
	s_add_u32 s58, s34, 0x40000
	v_lshl_add_u64 v[206:207], s[34:35], 0, v[198:199]
	s_addc_u32 s59, s35, 0
	s_add_i32 s60, s52, s40
	global_load_lds_dwordx4 v[206:207], off
	v_lshl_add_u64 v[208:209], s[58:59], 0, v[194:195]
	s_mov_b32 m0, s60
	v_lshl_add_u64 v[210:211], s[36:37], 0, v[196:197]
	global_load_lds_dwordx4 v[208:209], off
	v_lshl_add_u64 v[208:209], s[58:59], 0, v[198:199]
	s_add_i32 m0, s60, 0x2000
	s_nop 0
	global_load_lds_dwordx4 v[208:209], off
	v_lshl_add_u64 v[208:209], s[36:37], 0, v[192:193]
	s_mov_b32 m0, s41
	s_nop 0
	global_load_lds_dwordx4 v[208:209], off
	s_mov_b32 m0, s42
	s_nop 0
	global_load_lds_dwordx4 v[210:211], off
	s_waitcnt vmcnt(8)
	s_waitcnt lgkmcnt(0)
	s_barrier
; #define PG8_STAGE(bufoff, gbase, voff) do { _Pragma("unroll") for (int _i = 0; _i < 2; ++_i) \
;         __builtin_amdgcn_global_load_lds((const unsigned*)((const char*)(gbase) + (voff)[_i]), (PG8_LAS unsigned*)(lds + (bufoff) + ldsw + _i * 8192), 16, 0, 0); } while (0)
; #define PG8_LDA(dst, b, h) do { _Pragma("unroll") for (int m = 0; m < 4; ++m) _Pragma("unroll") for (int k = 0; k < 2; ++k) dst[m][k] = *(const PG8_LAS bf16x8*)(lds + PG8_SA(b, h) + aoff + m * 2048 + k * 1024); } while (0)
; #define PG8_LDB(dst, b, h) do { _Pragma("unroll") for (int n = 0; n < 2; ++n) _Pragma("unroll") for (int k = 0; k < 2; ++k) dst[n][k] = *(const PG8_LAS bf16x8*)(lds + PG8_SB(b, h) + boff + n * 2048 + k * 1024); } while (0)
; #define PG8_MMA(ai, bj, At, Bt) do { __builtin_amdgcn_s_setprio(1); _Pragma("unroll") for (int m = 0; m < 4; ++m) _Pragma("unroll") for (int n = 0; n < 2; ++n) _Pragma("unroll") for (int k = 0; k < 2; ++k) \
;         acc[ai][bj][m][n] = __builtin_amdgcn_mfma_f32_16x16x32_bf16(Bt[n][k], At[m][k], acc[ai][bj][m][n], 0, 0, 0); __builtin_amdgcn_s_setprio(0); } while (0)
; #define PG8_WAIT_V(n) asm volatile("s_waitcnt vmcnt(" #n ")" ::: "memory")
; #define PG8_WAIT_L(n) asm volatile("s_waitcnt lgkmcnt(" #n ")" ::: "memory")
; #define PG8_BAR __builtin_amdgcn_s_barrier()
; #define PG8_SCHED __builtin_amdgcn_sched_barrier(0)
; template <class Epi, class Sched, bool ALIGN_EPI = false, bool SP2 = false>
; __device__ __forceinline__ void gemm_phase(PG8_LAS unsigned char* lds, const Gemm g, const Sched& S, const Epi& E) {
;     ...
;             PG8_WAIT_V(8); PG8_WAIT_L(0); PG8_BAR; PG8_MMA(1, 0, At, B0); PG8_MMA(1, 1, At, B1); PG8_BAR; PG8_SCHED;
;             PG8_LDB(B0, 1, 0); PG8_LDB(B1, 1, 1); PG8_SCHED; PG8_LDA(At, 1, 0); PG8_STAGE(PG8_SA(0, 1), a2 + hstep, voffA);
;             PG8_WAIT_V(8); PG8_WAIT_L(0); PG8_BAR; PG8_MMA(0, 0, At, B0); PG8_MMA(0, 1, At, B1); PG8_BAR; PG8_SCHED;
	s_setprio 1
	s_waitcnt lgkmcnt(0)
	v_mfma_f32_16x16x32_bf16 v[60:63], v[120:123], v[160:163], v[60:63]
	v_mfma_f32_16x16x32_bf16 v[56:59], v[136:139], v[160:163], v[56:59]
	v_mfma_f32_16x16x32_bf16 v[44:47], v[120:123], v[168:171], v[44:47]
	v_mfma_f32_16x16x32_bf16 v[40:43], v[136:139], v[168:171], v[40:43]
	v_mfma_f32_16x16x32_bf16 v[28:31], v[120:123], v[176:179], v[28:31]
	v_mfma_f32_16x16x32_bf16 v[24:27], v[136:139], v[176:179], v[24:27]
	v_mfma_f32_16x16x32_bf16 v[12:15], v[120:123], v[184:187], v[12:15]
	v_mfma_f32_16x16x32_bf16 v[8:11], v[136:139], v[184:187], v[8:11]
	v_mfma_f32_16x16x32_bf16 v[60:63], v[128:131], v[164:167], v[60:63]
	v_mfma_f32_16x16x32_bf16 v[56:59], v[140:143], v[164:167], v[56:59]
	v_mfma_f32_16x16x32_bf16 v[44:47], v[128:131], v[172:175], v[44:47]
	v_mfma_f32_16x16x32_bf16 v[40:43], v[140:143], v[172:175], v[40:43]
	v_mfma_f32_16x16x32_bf16 v[28:31], v[128:131], v[180:183], v[28:31]
	v_mfma_f32_16x16x32_bf16 v[24:27], v[140:143], v[180:183], v[24:27]
	v_mfma_f32_16x16x32_bf16 v[12:15], v[128:131], v[188:191], v[12:15]
	v_mfma_f32_16x16x32_bf16 v[8:11], v[140:143], v[188:191], v[8:11]
	v_mfma_f32_16x16x32_bf16 v[52:55], v[144:147], v[160:163], v[52:55]
	v_mfma_f32_16x16x32_bf16 v[48:51], v[152:155], v[160:163], v[48:51]
	v_mfma_f32_16x16x32_bf16 v[36:39], v[144:147], v[168:171], v[36:39]
	v_mfma_f32_16x16x32_bf16 v[32:35], v[152:155], v[168:171], v[32:35]
	v_mfma_f32_16x16x32_bf16 v[20:23], v[144:147], v[176:179], v[20:23]
	v_mfma_f32_16x16x32_bf16 v[16:19], v[152:155], v[176:179], v[16:19]
	v_mfma_f32_16x16x32_bf16 v[4:7], v[144:147], v[184:187], v[4:7]
	v_mfma_f32_16x16x32_bf16 v[0:3], v[152:155], v[184:187], v[0:3]
	v_mfma_f32_16x16x32_bf16 v[52:55], v[148:151], v[164:167], v[52:55]
	v_mfma_f32_16x16x32_bf16 v[48:51], v[156:159], v[164:167], v[48:51]
	v_mfma_f32_16x16x32_bf16 v[36:39], v[148:151], v[172:175], v[36:39]
	v_mfma_f32_16x16x32_bf16 v[32:35], v[156:159], v[172:175], v[32:35]
	v_mfma_f32_16x16x32_bf16 v[20:23], v[148:151], v[180:183], v[20:23]
	v_mfma_f32_16x16x32_bf16 v[16:19], v[156:159], v[180:183], v[16:19]
	v_mfma_f32_16x16x32_bf16 v[4:7], v[148:151], v[188:191], v[4:7]
	v_mfma_f32_16x16x32_bf16 v[0:3], v[156:159], v[188:191], v[0:3]
	s_setprio 0
	s_barrier
	s_add_i32 s58, 0, 0x18000
	s_add_i32 s59, 0, 0x1c000
	v_add_u32_e32 v140, s58, v243
	v_add_u32_e32 v156, s59, v243
	ds_read_b128 v[120:123], v140
	ds_read_b128 v[128:131], v140 offset:1024
	ds_read_b128 v[136:139], v140 offset:2048
	ds_read_b128 v[140:143], v140 offset:3072
	ds_read_b128 v[144:147], v156
	ds_read_b128 v[148:151], v156 offset:1024
	ds_read_b128 v[152:155], v156 offset:2048
	ds_read_b128 v[156:159], v156 offset:3072
	s_add_u32 s36, s36, 0x40000
	s_addc_u32 s37, s37, 0
	s_mov_b32 m0, s43
	v_lshl_add_u64 v[212:213], s[36:37], 0, v[192:193]
	ds_read_b128 v[160:163], v247 offset:32768
	ds_read_b128 v[164:167], v247 offset:33792
	ds_read_b128 v[168:171], v247 offset:34816
	ds_read_b128 v[172:175], v247 offset:35840
	ds_read_b128 v[176:179], v247 offset:36864
	ds_read_b128 v[180:183], v247 offset:37888
	ds_read_b128 v[184:187], v247 offset:38912
	ds_read_b128 v[188:191], v247 offset:39936
	global_load_lds_dwordx4 v[212:213], off
	v_lshl_add_u64 v[212:213], s[36:37], 0, v[196:197]
	s_mov_b32 m0, s44
	s_nop 0
	global_load_lds_dwordx4 v[212:213], off
	s_waitcnt vmcnt(8)
	s_waitcnt lgkmcnt(0)
	s_barrier
	s_setprio 1
	s_waitcnt lgkmcnt(0)
	v_mfma_f32_16x16x32_bf16 v[132:135], v[120:123], v[160:163], v[132:135]
	v_mfma_f32_16x16x32_bf16 v[124:127], v[136:139], v[160:163], v[124:127]
	v_mfma_f32_16x16x32_bf16 v[108:111], v[120:123], v[168:171], v[108:111]
	v_mfma_f32_16x16x32_bf16 v[104:107], v[136:139], v[168:171], v[104:107]
	v_mfma_f32_16x16x32_bf16 v[92:95], v[120:123], v[176:179], v[92:95]
	v_mfma_f32_16x16x32_bf16 v[88:91], v[136:139], v[176:179], v[88:91]
	v_mfma_f32_16x16x32_bf16 v[76:79], v[120:123], v[184:187], v[76:79]
	v_mfma_f32_16x16x32_bf16 v[72:75], v[136:139], v[184:187], v[72:75]
	v_mfma_f32_16x16x32_bf16 v[132:135], v[128:131], v[164:167], v[132:135]
	v_mfma_f32_16x16x32_bf16 v[124:127], v[140:143], v[164:167], v[124:127]
	v_mfma_f32_16x16x32_bf16 v[108:111], v[128:131], v[172:175], v[108:111]
	v_mfma_f32_16x16x32_bf16 v[104:107], v[140:143], v[172:175], v[104:107]
	v_mfma_f32_16x16x32_bf16 v[92:95], v[128:131], v[180:183], v[92:95]
	v_mfma_f32_16x16x32_bf16 v[88:91], v[140:143], v[180:183], v[88:91]
	v_mfma_f32_16x16x32_bf16 v[76:79], v[128:131], v[188:191], v[76:79]
	v_mfma_f32_16x16x32_bf16 v[72:75], v[140:143], v[188:191], v[72:75]
	v_mfma_f32_16x16x32_bf16 v[116:119], v[144:147], v[160:163], v[116:119]
	v_mfma_f32_16x16x32_bf16 v[112:115], v[152:155], v[160:163], v[112:115]
	v_mfma_f32_16x16x32_bf16 v[100:103], v[144:147], v[168:171], v[100:103]
	v_mfma_f32_16x16x32_bf16 v[96:99], v[152:155], v[168:171], v[96:99]
	v_mfma_f32_16x16x32_bf16 v[84:87], v[144:147], v[176:179], v[84:87]
	v_mfma_f32_16x16x32_bf16 v[80:83], v[152:155], v[176:179], v[80:83]
	v_mfma_f32_16x16x32_bf16 v[68:71], v[144:147], v[184:187], v[68:71]
	v_mfma_f32_16x16x32_bf16 v[64:67], v[152:155], v[184:187], v[64:67]
	v_mfma_f32_16x16x32_bf16 v[116:119], v[148:151], v[164:167], v[116:119]
	v_mfma_f32_16x16x32_bf16 v[112:115], v[156:159], v[164:167], v[112:115]
	v_mfma_f32_16x16x32_bf16 v[100:103], v[148:151], v[172:175], v[100:103]
	v_mfma_f32_16x16x32_bf16 v[96:99], v[156:159], v[172:175], v[96:99]
	v_mfma_f32_16x16x32_bf16 v[84:87], v[148:151], v[180:183], v[84:87]
	v_mfma_f32_16x16x32_bf16 v[80:83], v[156:159], v[180:183], v[80:83]
	v_mfma_f32_16x16x32_bf16 v[68:71], v[148:151], v[188:191], v[68:71]
	v_mfma_f32_16x16x32_bf16 v[64:67], v[156:159], v[188:191], v[64:67]
	s_setprio 0
	s_barrier
; #define PG8_STAGE(bufoff, gbase, voff) do { _Pragma("unroll") for (int _i = 0; _i < 2; ++_i) \
;         __builtin_amdgcn_global_load_lds((const unsigned*)((const char*)(gbase) + (voff)[_i]), (PG8_LAS unsigned*)(lds + (bufoff) + ldsw + _i * 8192), 16, 0, 0); } while (0)
; #define PG8_LDA(dst, b, h) do { _Pragma("unroll") for (int m = 0; m < 4; ++m) _Pragma("unroll") for (int k = 0; k < 2; ++k) dst[m][k] = *(const PG8_LAS bf16x8*)(lds + PG8_SA(b, h) + aoff + m * 2048 + k * 1024); } while (0)
; #define PG8_MMA(ai, bj, At, Bt) do { __builtin_amdgcn_s_setprio(1); _Pragma("unroll") for (int m = 0; m < 4; ++m) _Pragma("unroll") for (int n = 0; n < 2; ++n) _Pragma("unroll") for (int k = 0; k < 2; ++k) \
;         acc[ai][bj][m][n] = __builtin_amdgcn_mfma_f32_16x16x32_bf16(Bt[n][k], At[m][k], acc[ai][bj][m][n], 0, 0, 0); __builtin_amdgcn_s_setprio(0); } while (0)
; #define PG8_WAIT_V(n) asm volatile("s_waitcnt vmcnt(" #n ")" ::: "memory")
; #define PG8_WAIT_L(n) asm volatile("s_waitcnt lgkmcnt(" #n ")" ::: "memory")
; #define PG8_BAR __builtin_amdgcn_s_barrier()
; #define PG8_SCHED __builtin_amdgcn_sched_barrier(0)
; template <class Epi, class Sched, bool ALIGN_EPI = false, bool SP2 = false>
; __device__ __forceinline__ void gemm_phase(PG8_LAS unsigned char* lds, const Gemm g, const Sched& S, const Epi& E) {
;     ...
;             PG8_LDA(At, 1, 1); PG8_STAGE(PG8_SB(1, 0), b3, voffB); PG8_STAGE(PG8_SB(1, 1), b3 + hstep, voffB); PG8_STAGE(PG8_SA(1, 0), a3, voffA);
;             PG8_WAIT_V(8); PG8_WAIT_L(0); PG8_BAR; PG8_MMA(1, 0, At, B0); PG8_MMA(1, 1, At, B1); PG8_BAR; PG8_SCHED;
;     ...
;         if constexpr (ALIGN_EPI) { if (wr == 0) PG8_BAR; }
;         if constexpr (!Epi::AFTER_DRAIN) { E(acc, cur, wr, wc, fr, fq, ui); S.done(cur); }
;         if (!has_next) break;
	s_add_i32 s36, s58, s40
	v_lshl_add_u64 v[204:205], v[204:205], 0, s[16:17]
	s_mov_b32 m0, s36
	ds_read_b128 v[160:163], v247 offset:49152
	ds_read_b128 v[164:167], v247 offset:50176
	ds_read_b128 v[168:171], v247 offset:51200
	ds_read_b128 v[172:175], v247 offset:52224
	ds_read_b128 v[176:179], v247 offset:53248
	ds_read_b128 v[180:183], v247 offset:54272
	ds_read_b128 v[184:187], v247 offset:55296
	ds_read_b128 v[188:191], v247 offset:56320
	global_load_lds_dwordx4 v[204:205], off
	s_add_i32 m0, s36, 0x2000
	s_add_u32 s34, s34, 0x40080
	v_lshl_add_u64 v[204:205], v[206:207], 0, s[16:17]
	s_addc_u32 s35, s35, 0
	s_add_i32 s36, s59, s40
	global_load_lds_dwordx4 v[204:205], off
	v_lshl_add_u64 v[204:205], s[34:35], 0, v[194:195]
	s_mov_b32 m0, s36
	s_nop 0
	global_load_lds_dwordx4 v[204:205], off
	v_lshl_add_u64 v[204:205], s[34:35], 0, v[198:199]
	s_add_i32 m0, s36, 0x2000
	s_nop 0
	global_load_lds_dwordx4 v[204:205], off
	v_lshl_add_u64 v[204:205], v[208:209], 0, s[16:17]
	s_mov_b32 m0, s46
	s_nop 0
	global_load_lds_dwordx4 v[204:205], off
	v_lshl_add_u64 v[204:205], v[210:211], 0, s[16:17]
	s_mov_b32 m0, s47
	s_nop 0
	global_load_lds_dwordx4 v[204:205], off
	s_waitcnt vmcnt(8)
	s_waitcnt lgkmcnt(0)
	s_barrier
	s_setprio 1
	s_waitcnt lgkmcnt(0)
	v_mfma_f32_16x16x32_bf16 v[60:63], v[120:123], v[160:163], v[60:63]
	v_mfma_f32_16x16x32_bf16 v[56:59], v[136:139], v[160:163], v[56:59]
	v_mfma_f32_16x16x32_bf16 v[44:47], v[120:123], v[168:171], v[44:47]
	v_mfma_f32_16x16x32_bf16 v[40:43], v[136:139], v[168:171], v[40:43]
	v_mfma_f32_16x16x32_bf16 v[28:31], v[120:123], v[176:179], v[28:31]
	v_mfma_f32_16x16x32_bf16 v[24:27], v[136:139], v[176:179], v[24:27]
	v_mfma_f32_16x16x32_bf16 v[12:15], v[120:123], v[184:187], v[12:15]
	v_mfma_f32_16x16x32_bf16 v[8:11], v[136:139], v[184:187], v[8:11]
	v_mfma_f32_16x16x32_bf16 v[60:63], v[128:131], v[164:167], v[60:63]
	v_mfma_f32_16x16x32_bf16 v[56:59], v[140:143], v[164:167], v[56:59]
	v_mfma_f32_16x16x32_bf16 v[44:47], v[128:131], v[172:175], v[44:47]
	v_mfma_f32_16x16x32_bf16 v[40:43], v[140:143], v[172:175], v[40:43]
	v_mfma_f32_16x16x32_bf16 v[28:31], v[128:131], v[180:183], v[28:31]
	v_mfma_f32_16x16x32_bf16 v[24:27], v[140:143], v[180:183], v[24:27]
	v_mfma_f32_16x16x32_bf16 v[12:15], v[128:131], v[188:191], v[12:15]
	v_mfma_f32_16x16x32_bf16 v[8:11], v[140:143], v[188:191], v[8:11]
	v_mfma_f32_16x16x32_bf16 v[52:55], v[144:147], v[160:163], v[52:55]
	v_mfma_f32_16x16x32_bf16 v[48:51], v[152:155], v[160:163], v[48:51]
	v_mfma_f32_16x16x32_bf16 v[36:39], v[144:147], v[168:171], v[36:39]
	v_mfma_f32_16x16x32_bf16 v[32:35], v[152:155], v[168:171], v[32:35]
	v_mfma_f32_16x16x32_bf16 v[20:23], v[144:147], v[176:179], v[20:23]
	v_mfma_f32_16x16x32_bf16 v[16:19], v[152:155], v[176:179], v[16:19]
	v_mfma_f32_16x16x32_bf16 v[4:7], v[144:147], v[184:187], v[4:7]
	v_mfma_f32_16x16x32_bf16 v[0:3], v[152:155], v[184:187], v[0:3]
	v_mfma_f32_16x16x32_bf16 v[52:55], v[148:151], v[164:167], v[52:55]
	v_mfma_f32_16x16x32_bf16 v[48:51], v[156:159], v[164:167], v[48:51]
	v_mfma_f32_16x16x32_bf16 v[36:39], v[148:151], v[172:175], v[36:39]
	v_mfma_f32_16x16x32_bf16 v[32:35], v[156:159], v[172:175], v[32:35]
	v_mfma_f32_16x16x32_bf16 v[20:23], v[148:151], v[180:183], v[20:23]
	v_mfma_f32_16x16x32_bf16 v[16:19], v[156:159], v[180:183], v[16:19]
	v_mfma_f32_16x16x32_bf16 v[4:7], v[148:151], v[188:191], v[4:7]
	v_mfma_f32_16x16x32_bf16 v[0:3], v[156:159], v[188:191], v[0:3]
	s_setprio 0
	s_barrier
	s_add_i32 s57, s57, 2
	s_add_u32 s30, s30, 0x100
	s_addc_u32 s31, s31, 0
	s_add_u32 s55, s55, 0x100
	s_addc_u32 s56, s56, 0
	s_cmp_gt_u32 s57, 13
	s_cbranch_scc0 .LBB0_960
	s_and_b64 vcc, exec, s[18:19]
	s_cbranch_vccz .LBB0_963
	s_barrier

; #define PG8_STAGE(bufoff, gbase, voff) do { _Pragma("unroll") for (int _i = 0; _i < 2; ++_i) \
;         __builtin_amdgcn_global_load_lds((const unsigned*)((const char*)(gbase) + (voff)[_i]), (PG8_LAS unsigned*)(lds + (bufoff) + ldsw + _i * 8192), 16, 0, 0); } while (0)
; #define PG8_LDA(dst, b, h) do { _Pragma("unroll") for (int m = 0; m < 4; ++m) _Pragma("unroll") for (int k = 0; k < 2; ++k) dst[m][k] = *(const PG8_LAS bf16x8*)(lds + PG8_SA(b, h) + aoff + m * 2048 + k * 1024); } while (0)
; #define PG8_LDB(dst, b, h) do { _Pragma("unroll") for (int n = 0; n < 2; ++n) _Pragma("unroll") for (int k = 0; k < 2; ++k) dst[n][k] = *(const PG8_LAS bf16x8*)(lds + PG8_SB(b, h) + boff + n * 2048 + k * 1024); } while (0)
; #define PG8_MMA(ai, bj, At, Bt) do { __builtin_amdgcn_s_setprio(1); _Pragma("unroll") for (int m = 0; m < 4; ++m) _Pragma("unroll") for (int n = 0; n < 2; ++n) _Pragma("unroll") for (int k = 0; k < 2; ++k) \
;         acc[ai][bj][m][n] = __builtin_amdgcn_mfma_f32_16x16x32_bf16(Bt[n][k], At[m][k], acc[ai][bj][m][n], 0, 0, 0); __builtin_amdgcn_s_setprio(0); } while (0)
; #define PG8_WAIT_V(n) asm volatile("s_waitcnt vmcnt(" #n ")" ::: "memory")
; #define PG8_WAIT_L(n) asm volatile("s_waitcnt lgkmcnt(" #n ")" ::: "memory")
; #define PG8_BAR __builtin_amdgcn_s_barrier()
; #define PG8_SCHED __builtin_amdgcn_sched_barrier(0)
; template <class Epi, class Sched, bool ALIGN_EPI = false, bool SP2 = false>
; __device__ __forceinline__ void gemm_phase(PG8_LAS unsigned char* lds, const Gemm g, const Sched& S, const Epi& E) {
;     ...
;             PG8_LDB(B0, 0, 0); PG8_LDB(B1, 0, 1); PG8_SCHED; PG8_LDA(At, 0, 0); PG8_STAGE(PG8_SA(1, 1), a1 + hstep, voffA);
;             PG8_WAIT_V(8); PG8_WAIT_L(0); PG8_BAR; PG8_MMA(0, 0, At, B0); PG8_MMA(0, 1, At, B1); PG8_BAR; PG8_SCHED;
;             PG8_LDA(At, 0, 1); PG8_STAGE(PG8_SB(0, 0), b2, voffB); PG8_STAGE(PG8_SB(0, 1), b2 + hstep, voffB); PG8_STAGE(PG8_SA(0, 0), a2, voffA);
;             PG8_WAIT_V(8); PG8_WAIT_L(0); PG8_BAR; PG8_MMA(1, 0, At, B0); PG8_MMA(1, 1, At, B1); PG8_BAR; PG8_SCHED;
.LBB0_1219:
	ds_read_b128 v[152:155], v148
	ds_read_b128 v[156:159], v148 offset:1024
	ds_read_b128 v[160:163], v148 offset:2048
	ds_read_b128 v[164:167], v148 offset:3072
	ds_read_b128 v[168:171], v149
	ds_read_b128 v[172:175], v149 offset:1024
	ds_read_b128 v[176:179], v149 offset:2048
	ds_read_b128 v[180:183], v149 offset:3072
	s_add_u32 s26, s24, 0xfffc0080
	s_addc_u32 s27, s25, -1
	s_cmp_eq_u32 s54, 12
	s_cselect_b32 s29, s17, s27
	s_cselect_b32 s28, s50, s26
	s_cselect_b32 s27, s15, s53
	s_cselect_b32 s26, s51, s52
	v_lshl_add_u64 v[216:217], s[24:25], 0, v[136:137]
	s_add_i32 m0, s23, 0xc000
	ds_read_b128 v[184:187], v150
	ds_read_b128 v[188:191], v150 offset:1024
	ds_read_b128 v[192:195], v150 offset:2048
	ds_read_b128 v[196:199], v150 offset:3072
	ds_read_b128 v[200:203], v150 offset:4096
	ds_read_b128 v[204:207], v150 offset:5120
	ds_read_b128 v[208:211], v150 offset:6144
	ds_read_b128 v[212:215], v150 offset:7168
	global_load_lds_dwordx4 v[216:217], off
	v_lshl_add_u64 v[216:217], s[24:25], 0, v[138:139]
	s_add_i32 m0, s23, 0xe000
	s_nop 0
	global_load_lds_dwordx4 v[216:217], off
	s_waitcnt vmcnt(8)
	s_waitcnt lgkmcnt(0)
	s_barrier
	s_setprio 1
	s_waitcnt lgkmcnt(0)
	v_mfma_f32_16x16x32_bf16 v[124:127], v[152:155], v[184:187], v[124:127]
	v_mfma_f32_16x16x32_bf16 v[120:123], v[160:163], v[184:187], v[120:123]
	v_mfma_f32_16x16x32_bf16 v[108:111], v[152:155], v[192:195], v[108:111]
	v_mfma_f32_16x16x32_bf16 v[104:107], v[160:163], v[192:195], v[104:107]
	v_mfma_f32_16x16x32_bf16 v[92:95], v[152:155], v[200:203], v[92:95]
	v_mfma_f32_16x16x32_bf16 v[88:91], v[160:163], v[200:203], v[88:91]
	v_mfma_f32_16x16x32_bf16 v[76:79], v[152:155], v[208:211], v[76:79]
	v_mfma_f32_16x16x32_bf16 v[72:75], v[160:163], v[208:211], v[72:75]
	v_mfma_f32_16x16x32_bf16 v[124:127], v[156:159], v[188:191], v[124:127]
	v_mfma_f32_16x16x32_bf16 v[120:123], v[164:167], v[188:191], v[120:123]
	v_mfma_f32_16x16x32_bf16 v[108:111], v[156:159], v[196:199], v[108:111]
	v_mfma_f32_16x16x32_bf16 v[104:107], v[164:167], v[196:199], v[104:107]
	v_mfma_f32_16x16x32_bf16 v[92:95], v[156:159], v[204:207], v[92:95]
	v_mfma_f32_16x16x32_bf16 v[88:91], v[164:167], v[204:207], v[88:91]
	v_mfma_f32_16x16x32_bf16 v[76:79], v[156:159], v[212:215], v[76:79]
	v_mfma_f32_16x16x32_bf16 v[72:75], v[164:167], v[212:215], v[72:75]
	v_mfma_f32_16x16x32_bf16 v[116:119], v[168:171], v[184:187], v[116:119]
	v_mfma_f32_16x16x32_bf16 v[112:115], v[176:179], v[184:187], v[112:115]
	v_mfma_f32_16x16x32_bf16 v[100:103], v[168:171], v[192:195], v[100:103]
	v_mfma_f32_16x16x32_bf16 v[96:99], v[176:179], v[192:195], v[96:99]
	v_mfma_f32_16x16x32_bf16 v[84:87], v[168:171], v[200:203], v[84:87]
	v_mfma_f32_16x16x32_bf16 v[80:83], v[176:179], v[200:203], v[80:83]
	v_mfma_f32_16x16x32_bf16 v[68:71], v[168:171], v[208:211], v[68:71]
	v_mfma_f32_16x16x32_bf16 v[64:67], v[176:179], v[208:211], v[64:67]
	v_mfma_f32_16x16x32_bf16 v[116:119], v[172:175], v[188:191], v[116:119]
	v_mfma_f32_16x16x32_bf16 v[112:115], v[180:183], v[188:191], v[112:115]
	v_mfma_f32_16x16x32_bf16 v[100:103], v[172:175], v[196:199], v[100:103]
	v_mfma_f32_16x16x32_bf16 v[96:99], v[180:183], v[196:199], v[96:99]
	v_mfma_f32_16x16x32_bf16 v[84:87], v[172:175], v[204:207], v[84:87]
	v_mfma_f32_16x16x32_bf16 v[80:83], v[180:183], v[204:207], v[80:83]
	v_mfma_f32_16x16x32_bf16 v[68:71], v[172:175], v[212:215], v[68:71]
	v_mfma_f32_16x16x32_bf16 v[64:67], v[180:183], v[212:215], v[64:67]
	s_setprio 0
	s_barrier
	s_add_i32 s55, s44, s33
	v_lshl_add_u64 v[216:217], s[26:27], 0, v[132:133]
	s_mov_b32 m0, s55
	ds_read_b128 v[184:187], v150 offset:16384
	ds_read_b128 v[188:191], v150 offset:17408
	ds_read_b128 v[192:195], v150 offset:18432
	ds_read_b128 v[196:199], v150 offset:19456
	ds_read_b128 v[200:203], v150 offset:20480
	ds_read_b128 v[204:207], v150 offset:21504
	ds_read_b128 v[208:211], v150 offset:22528
	ds_read_b128 v[212:215], v150 offset:23552
	global_load_lds_dwordx4 v[216:217], off
	s_add_i32 m0, s55, 0x2000
	s_add_u32 s56, s26, 0x40000
	v_lshl_add_u64 v[218:219], s[26:27], 0, v[128:129]
	s_addc_u32 s57, s27, 0
	s_add_i32 s55, s45, s33
	global_load_lds_dwordx4 v[218:219], off
	v_lshl_add_u64 v[220:221], s[56:57], 0, v[132:133]
	s_mov_b32 m0, s55
	v_lshl_add_u64 v[222:223], s[28:29], 0, v[130:131]
	global_load_lds_dwordx4 v[220:221], off
	v_lshl_add_u64 v[220:221], s[56:57], 0, v[128:129]
	s_add_i32 m0, s55, 0x2000
	s_nop 0
	global_load_lds_dwordx4 v[220:221], off
	v_lshl_add_u64 v[220:221], s[28:29], 0, v[134:135]
	s_mov_b32 m0, s23
	s_nop 0
	global_load_lds_dwordx4 v[220:221], off
	s_mov_b32 m0, s39
	s_nop 0
	global_load_lds_dwordx4 v[222:223], off
	s_waitcnt vmcnt(8)
	s_waitcnt lgkmcnt(0)
	s_barrier
; #define PG8_STAGE(bufoff, gbase, voff) do { _Pragma("unroll") for (int _i = 0; _i < 2; ++_i) \
;         __builtin_amdgcn_global_load_lds((const unsigned*)((const char*)(gbase) + (voff)[_i]), (PG8_LAS unsigned*)(lds + (bufoff) + ldsw + _i * 8192), 16, 0, 0); } while (0)
; #define PG8_LDA(dst, b, h) do { _Pragma("unroll") for (int m = 0; m < 4; ++m) _Pragma("unroll") for (int k = 0; k < 2; ++k) dst[m][k] = *(const PG8_LAS bf16x8*)(lds + PG8_SA(b, h) + aoff + m * 2048 + k * 1024); } while (0)
; #define PG8_LDB(dst, b, h) do { _Pragma("unroll") for (int n = 0; n < 2; ++n) _Pragma("unroll") for (int k = 0; k < 2; ++k) dst[n][k] = *(const PG8_LAS bf16x8*)(lds + PG8_SB(b, h) + boff + n * 2048 + k * 1024); } while (0)
; #define PG8_MMA(ai, bj, At, Bt) do { __builtin_amdgcn_s_setprio(1); _Pragma("unroll") for (int m = 0; m < 4; ++m) _Pragma("unroll") for (int n = 0; n < 2; ++n) _Pragma("unroll") for (int k = 0; k < 2; ++k) \
;         acc[ai][bj][m][n] = __builtin_amdgcn_mfma_f32_16x16x32_bf16(Bt[n][k], At[m][k], acc[ai][bj][m][n], 0, 0, 0); __builtin_amdgcn_s_setprio(0); } while (0)
; #define PG8_WAIT_V(n) asm volatile("s_waitcnt vmcnt(" #n ")" ::: "memory")
; #define PG8_WAIT_L(n) asm volatile("s_waitcnt lgkmcnt(" #n ")" ::: "memory")
; #define PG8_BAR __builtin_amdgcn_s_barrier()
; #define PG8_SCHED __builtin_amdgcn_sched_barrier(0)
; template <class Epi, class Sched, bool ALIGN_EPI = false, bool SP2 = false>
; __device__ __forceinline__ void gemm_phase(PG8_LAS unsigned char* lds, const Gemm g, const Sched& S, const Epi& E) {
;     ...
;             PG8_WAIT_V(8); PG8_WAIT_L(0); PG8_BAR; PG8_MMA(1, 0, At, B0); PG8_MMA(1, 1, At, B1); PG8_BAR; PG8_SCHED;
;             PG8_LDB(B0, 1, 0); PG8_LDB(B1, 1, 1); PG8_SCHED; PG8_LDA(At, 1, 0); PG8_STAGE(PG8_SA(0, 1), a2 + hstep, voffA);
;             PG8_WAIT_V(8); PG8_WAIT_L(0); PG8_BAR; PG8_MMA(0, 0, At, B0); PG8_MMA(0, 1, At, B1); PG8_BAR; PG8_SCHED;
	s_setprio 1
	s_waitcnt lgkmcnt(0)
	v_mfma_f32_16x16x32_bf16 v[60:63], v[152:155], v[184:187], v[60:63]
	v_mfma_f32_16x16x32_bf16 v[56:59], v[160:163], v[184:187], v[56:59]
	v_mfma_f32_16x16x32_bf16 v[44:47], v[152:155], v[192:195], v[44:47]
	v_mfma_f32_16x16x32_bf16 v[40:43], v[160:163], v[192:195], v[40:43]
	v_mfma_f32_16x16x32_bf16 v[28:31], v[152:155], v[200:203], v[28:31]
	v_mfma_f32_16x16x32_bf16 v[24:27], v[160:163], v[200:203], v[24:27]
	v_mfma_f32_16x16x32_bf16 v[12:15], v[152:155], v[208:211], v[12:15]
	v_mfma_f32_16x16x32_bf16 v[8:11], v[160:163], v[208:211], v[8:11]
	v_mfma_f32_16x16x32_bf16 v[60:63], v[156:159], v[188:191], v[60:63]
	v_mfma_f32_16x16x32_bf16 v[56:59], v[164:167], v[188:191], v[56:59]
	v_mfma_f32_16x16x32_bf16 v[44:47], v[156:159], v[196:199], v[44:47]
	v_mfma_f32_16x16x32_bf16 v[40:43], v[164:167], v[196:199], v[40:43]
	v_mfma_f32_16x16x32_bf16 v[28:31], v[156:159], v[204:207], v[28:31]
	v_mfma_f32_16x16x32_bf16 v[24:27], v[164:167], v[204:207], v[24:27]
	v_mfma_f32_16x16x32_bf16 v[12:15], v[156:159], v[212:215], v[12:15]
	v_mfma_f32_16x16x32_bf16 v[8:11], v[164:167], v[212:215], v[8:11]
	v_mfma_f32_16x16x32_bf16 v[52:55], v[168:171], v[184:187], v[52:55]
	v_mfma_f32_16x16x32_bf16 v[48:51], v[176:179], v[184:187], v[48:51]
	v_mfma_f32_16x16x32_bf16 v[36:39], v[168:171], v[192:195], v[36:39]
	v_mfma_f32_16x16x32_bf16 v[32:35], v[176:179], v[192:195], v[32:35]
	v_mfma_f32_16x16x32_bf16 v[20:23], v[168:171], v[200:203], v[20:23]
	v_mfma_f32_16x16x32_bf16 v[16:19], v[176:179], v[200:203], v[16:19]
	v_mfma_f32_16x16x32_bf16 v[4:7], v[168:171], v[208:211], v[4:7]
	v_mfma_f32_16x16x32_bf16 v[0:3], v[176:179], v[208:211], v[0:3]
	v_mfma_f32_16x16x32_bf16 v[52:55], v[172:175], v[188:191], v[52:55]
	v_mfma_f32_16x16x32_bf16 v[48:51], v[180:183], v[188:191], v[48:51]
	v_mfma_f32_16x16x32_bf16 v[36:39], v[172:175], v[196:199], v[36:39]
	v_mfma_f32_16x16x32_bf16 v[32:35], v[180:183], v[196:199], v[32:35]
	v_mfma_f32_16x16x32_bf16 v[20:23], v[172:175], v[204:207], v[20:23]
	v_mfma_f32_16x16x32_bf16 v[16:19], v[180:183], v[204:207], v[16:19]
	v_mfma_f32_16x16x32_bf16 v[4:7], v[172:175], v[212:215], v[4:7]
	v_mfma_f32_16x16x32_bf16 v[0:3], v[180:183], v[212:215], v[0:3]
	s_setprio 0
	s_barrier
	s_add_i32 s55, 0, 0x18000
	v_add_u32_e32 v151, s55, v145
	s_add_i32 s56, 0, 0x1c000
	ds_read_b128 v[152:155], v151
	ds_read_b128 v[156:159], v151 offset:1024
	ds_read_b128 v[160:163], v151 offset:2048
	ds_read_b128 v[164:167], v151 offset:3072
	v_add_u32_e32 v151, s56, v145
	ds_read_b128 v[168:171], v151
	ds_read_b128 v[172:175], v151 offset:1024
	ds_read_b128 v[176:179], v151 offset:2048
	ds_read_b128 v[180:183], v151 offset:3072
	s_add_u32 s28, s28, 0x40000
	s_addc_u32 s29, s29, 0
	s_mov_b32 m0, s40
	v_lshl_add_u64 v[224:225], s[28:29], 0, v[134:135]
	ds_read_b128 v[184:187], v150 offset:32768
	ds_read_b128 v[188:191], v150 offset:33792
	ds_read_b128 v[192:195], v150 offset:34816
	ds_read_b128 v[196:199], v150 offset:35840
	ds_read_b128 v[200:203], v150 offset:36864
	ds_read_b128 v[204:207], v150 offset:37888
	ds_read_b128 v[208:211], v150 offset:38912
	ds_read_b128 v[212:215], v150 offset:39936
	global_load_lds_dwordx4 v[224:225], off
	v_lshl_add_u64 v[224:225], s[28:29], 0, v[130:131]
	s_mov_b32 m0, s41
	s_nop 0
	global_load_lds_dwordx4 v[224:225], off
	s_waitcnt vmcnt(8)
	s_waitcnt lgkmcnt(0)
	s_barrier
	s_setprio 1
	s_waitcnt lgkmcnt(0)
	v_mfma_f32_16x16x32_bf16 v[124:127], v[152:155], v[184:187], v[124:127]
	v_mfma_f32_16x16x32_bf16 v[120:123], v[160:163], v[184:187], v[120:123]
	v_mfma_f32_16x16x32_bf16 v[108:111], v[152:155], v[192:195], v[108:111]
	v_mfma_f32_16x16x32_bf16 v[104:107], v[160:163], v[192:195], v[104:107]
	v_mfma_f32_16x16x32_bf16 v[92:95], v[152:155], v[200:203], v[92:95]
	v_mfma_f32_16x16x32_bf16 v[88:91], v[160:163], v[200:203], v[88:91]
	v_mfma_f32_16x16x32_bf16 v[76:79], v[152:155], v[208:211], v[76:79]
	v_mfma_f32_16x16x32_bf16 v[72:75], v[160:163], v[208:211], v[72:75]
	v_mfma_f32_16x16x32_bf16 v[124:127], v[156:159], v[188:191], v[124:127]
	v_mfma_f32_16x16x32_bf16 v[120:123], v[164:167], v[188:191], v[120:123]
	v_mfma_f32_16x16x32_bf16 v[108:111], v[156:159], v[196:199], v[108:111]
	v_mfma_f32_16x16x32_bf16 v[104:107], v[164:167], v[196:199], v[104:107]
	v_mfma_f32_16x16x32_bf16 v[92:95], v[156:159], v[204:207], v[92:95]
	v_mfma_f32_16x16x32_bf16 v[88:91], v[164:167], v[204:207], v[88:91]
	v_mfma_f32_16x16x32_bf16 v[76:79], v[156:159], v[212:215], v[76:79]
	v_mfma_f32_16x16x32_bf16 v[72:75], v[164:167], v[212:215], v[72:75]
	v_mfma_f32_16x16x32_bf16 v[116:119], v[168:171], v[184:187], v[116:119]
	v_mfma_f32_16x16x32_bf16 v[112:115], v[176:179], v[184:187], v[112:115]
	v_mfma_f32_16x16x32_bf16 v[100:103], v[168:171], v[192:195], v[100:103]
	v_mfma_f32_16x16x32_bf16 v[96:99], v[176:179], v[192:195], v[96:99]
	v_mfma_f32_16x16x32_bf16 v[84:87], v[168:171], v[200:203], v[84:87]
	v_mfma_f32_16x16x32_bf16 v[80:83], v[176:179], v[200:203], v[80:83]
	v_mfma_f32_16x16x32_bf16 v[68:71], v[168:171], v[208:211], v[68:71]
	v_mfma_f32_16x16x32_bf16 v[64:67], v[176:179], v[208:211], v[64:67]
	v_mfma_f32_16x16x32_bf16 v[116:119], v[172:175], v[188:191], v[116:119]
	v_mfma_f32_16x16x32_bf16 v[112:115], v[180:183], v[188:191], v[112:115]
	v_mfma_f32_16x16x32_bf16 v[100:103], v[172:175], v[196:199], v[100:103]
	v_mfma_f32_16x16x32_bf16 v[96:99], v[180:183], v[196:199], v[96:99]
	v_mfma_f32_16x16x32_bf16 v[84:87], v[172:175], v[204:207], v[84:87]
	v_mfma_f32_16x16x32_bf16 v[80:83], v[180:183], v[204:207], v[80:83]
	v_mfma_f32_16x16x32_bf16 v[68:71], v[172:175], v[212:215], v[68:71]
	v_mfma_f32_16x16x32_bf16 v[64:67], v[180:183], v[212:215], v[64:67]
	s_setprio 0
	s_barrier
; #define PG8_STAGE(bufoff, gbase, voff) do { _Pragma("unroll") for (int _i = 0; _i < 2; ++_i) \
;         __builtin_amdgcn_global_load_lds((const unsigned*)((const char*)(gbase) + (voff)[_i]), (PG8_LAS unsigned*)(lds + (bufoff) + ldsw + _i * 8192), 16, 0, 0); } while (0)
; #define PG8_LDA(dst, b, h) do { _Pragma("unroll") for (int m = 0; m < 4; ++m) _Pragma("unroll") for (int k = 0; k < 2; ++k) dst[m][k] = *(const PG8_LAS bf16x8*)(lds + PG8_SA(b, h) + aoff + m * 2048 + k * 1024); } while (0)
; #define PG8_MMA(ai, bj, At, Bt) do { __builtin_amdgcn_s_setprio(1); _Pragma("unroll") for (int m = 0; m < 4; ++m) _Pragma("unroll") for (int n = 0; n < 2; ++n) _Pragma("unroll") for (int k = 0; k < 2; ++k) \
;         acc[ai][bj][m][n] = __builtin_amdgcn_mfma_f32_16x16x32_bf16(Bt[n][k], At[m][k], acc[ai][bj][m][n], 0, 0, 0); __builtin_amdgcn_s_setprio(0); } while (0)
; #define PG8_WAIT_V(n) asm volatile("s_waitcnt vmcnt(" #n ")" ::: "memory")
; #define PG8_WAIT_L(n) asm volatile("s_waitcnt lgkmcnt(" #n ")" ::: "memory")
; #define PG8_BAR __builtin_amdgcn_s_barrier()
; #define PG8_SCHED __builtin_amdgcn_sched_barrier(0)
; template <class Epi, class Sched, bool ALIGN_EPI = false, bool SP2 = false>
; __device__ __forceinline__ void gemm_phase(PG8_LAS unsigned char* lds, const Gemm g, const Sched& S, const Epi& E) {
;     ...
;         for (int t = 0; t < nt; t += 2) {
;     ...
;             PG8_LDA(At, 1, 1); PG8_STAGE(PG8_SB(1, 0), b3, voffB); PG8_STAGE(PG8_SB(1, 1), b3 + hstep, voffB); PG8_STAGE(PG8_SA(1, 0), a3, voffA);
;             PG8_WAIT_V(8); PG8_WAIT_L(0); PG8_BAR; PG8_MMA(1, 0, At, B0); PG8_MMA(1, 1, At, B1); PG8_BAR; PG8_SCHED;
	s_add_i32 s28, s55, s33
	v_lshl_add_u64 v[216:217], v[216:217], 0, s[10:11]
	s_mov_b32 m0, s28
	ds_read_b128 v[184:187], v150 offset:49152
	ds_read_b128 v[188:191], v150 offset:50176
	ds_read_b128 v[192:195], v150 offset:51200
	ds_read_b128 v[196:199], v150 offset:52224
	ds_read_b128 v[200:203], v150 offset:53248
	ds_read_b128 v[204:207], v150 offset:54272
	ds_read_b128 v[208:211], v150 offset:55296
	ds_read_b128 v[212:215], v150 offset:56320
	global_load_lds_dwordx4 v[216:217], off
	s_add_i32 m0, s28, 0x2000
	s_add_u32 s26, s26, 0x40080
	v_lshl_add_u64 v[216:217], v[218:219], 0, s[10:11]
	s_addc_u32 s27, s27, 0
	s_add_i32 s28, s56, s33
	global_load_lds_dwordx4 v[216:217], off
	v_lshl_add_u64 v[216:217], s[26:27], 0, v[132:133]
	s_mov_b32 m0, s28
	s_nop 0
	global_load_lds_dwordx4 v[216:217], off
	v_lshl_add_u64 v[216:217], s[26:27], 0, v[128:129]
	s_add_i32 m0, s28, 0x2000
	s_nop 0
	global_load_lds_dwordx4 v[216:217], off
	v_lshl_add_u64 v[216:217], v[220:221], 0, s[10:11]
	s_mov_b32 m0, s42
	s_nop 0
	global_load_lds_dwordx4 v[216:217], off
	v_lshl_add_u64 v[216:217], v[222:223], 0, s[10:11]
	s_mov_b32 m0, s43
	s_nop 0
	global_load_lds_dwordx4 v[216:217], off
	s_waitcnt vmcnt(8)
	s_waitcnt lgkmcnt(0)
	s_barrier
	s_setprio 1
	s_waitcnt lgkmcnt(0)
	v_mfma_f32_16x16x32_bf16 v[60:63], v[152:155], v[184:187], v[60:63]
	v_mfma_f32_16x16x32_bf16 v[56:59], v[160:163], v[184:187], v[56:59]
	v_mfma_f32_16x16x32_bf16 v[44:47], v[152:155], v[192:195], v[44:47]
	v_mfma_f32_16x16x32_bf16 v[40:43], v[160:163], v[192:195], v[40:43]
	v_mfma_f32_16x16x32_bf16 v[28:31], v[152:155], v[200:203], v[28:31]
	v_mfma_f32_16x16x32_bf16 v[24:27], v[160:163], v[200:203], v[24:27]
	v_mfma_f32_16x16x32_bf16 v[12:15], v[152:155], v[208:211], v[12:15]
	v_mfma_f32_16x16x32_bf16 v[8:11], v[160:163], v[208:211], v[8:11]
	v_mfma_f32_16x16x32_bf16 v[60:63], v[156:159], v[188:191], v[60:63]
	v_mfma_f32_16x16x32_bf16 v[56:59], v[164:167], v[188:191], v[56:59]
	v_mfma_f32_16x16x32_bf16 v[44:47], v[156:159], v[196:199], v[44:47]
	v_mfma_f32_16x16x32_bf16 v[40:43], v[164:167], v[196:199], v[40:43]
	v_mfma_f32_16x16x32_bf16 v[28:31], v[156:159], v[204:207], v[28:31]
	v_mfma_f32_16x16x32_bf16 v[24:27], v[164:167], v[204:207], v[24:27]
	v_mfma_f32_16x16x32_bf16 v[12:15], v[156:159], v[212:215], v[12:15]
	v_mfma_f32_16x16x32_bf16 v[8:11], v[164:167], v[212:215], v[8:11]
	v_mfma_f32_16x16x32_bf16 v[52:55], v[168:171], v[184:187], v[52:55]
	v_mfma_f32_16x16x32_bf16 v[48:51], v[176:179], v[184:187], v[48:51]
	v_mfma_f32_16x16x32_bf16 v[36:39], v[168:171], v[192:195], v[36:39]
	v_mfma_f32_16x16x32_bf16 v[32:35], v[176:179], v[192:195], v[32:35]
	v_mfma_f32_16x16x32_bf16 v[20:23], v[168:171], v[200:203], v[20:23]
	v_mfma_f32_16x16x32_bf16 v[16:19], v[176:179], v[200:203], v[16:19]
	v_mfma_f32_16x16x32_bf16 v[4:7], v[168:171], v[208:211], v[4:7]
	v_mfma_f32_16x16x32_bf16 v[0:3], v[176:179], v[208:211], v[0:3]
	v_mfma_f32_16x16x32_bf16 v[52:55], v[172:175], v[188:191], v[52:55]
	v_mfma_f32_16x16x32_bf16 v[48:51], v[180:183], v[188:191], v[48:51]
	v_mfma_f32_16x16x32_bf16 v[36:39], v[172:175], v[196:199], v[36:39]
	v_mfma_f32_16x16x32_bf16 v[32:35], v[180:183], v[196:199], v[32:35]
	v_mfma_f32_16x16x32_bf16 v[20:23], v[172:175], v[204:207], v[20:23]
	v_mfma_f32_16x16x32_bf16 v[16:19], v[180:183], v[204:207], v[16:19]
	v_mfma_f32_16x16x32_bf16 v[4:7], v[172:175], v[212:215], v[4:7]
	v_mfma_f32_16x16x32_bf16 v[0:3], v[180:183], v[212:215], v[0:3]
	s_setprio 0
	s_barrier
	s_add_i32 s54, s54, 2
	s_add_u32 s24, s24, 0x100
	s_addc_u32 s25, s25, 0
	s_add_u32 s52, s52, 0x100
	s_addc_u32 s53, s53, 0
	s_cmp_gt_u32 s54, 13
	s_cbranch_scc0 .LBB0_1219
	s_and_b64 vcc, exec, s[12:13]
	s_cbranch_vccz .LBB0_1222
	s_barrier
